# kernarg pointers of the prep item loop and the prompt-scan loop preloaded into SGPRs; output-phase trip-top waits count the previous trip's two stores
# speedup vs baseline: 1.0156x; 1.0156x over previous
; __device__ __forceinline__ void phase_prep(const Params& p, unsigned char* shm) {
;     constexpr int LD = 72, LZH = 136, LZS = 200;
;     bf16_t* thw = (bf16_t*)shm; bf16_t* tha = thw + 64 * LD; bf16_t* w2T = tha + 64 * LD; bf16_t* a2T = w2T + 64 * LD;
;     float* Aab = (float*)shm;
;     bf16_t* Tm = (bf16_t*)(shm + 17408); bf16_t* VKt = Tm + 64 * LD;
;     bf16_t* Qt = (bf16_t*)(shm + 36864); bf16_t* Kt = Qt + 64 * LD; bf16_t* Bt = Kt + 64 * LD; bf16_t* KKt = Bt + 64 * LD;
;     bf16_t* zh = Qt;
;     bf16_t* zs = (bf16_t*)(shm + 36864 + 65 * LZH * 2);
;     bf16_t* XT = KKt;
;     bf16_t* TT = (bf16_t*)(shm + 152064); bf16_t* ET = TT + 64 * LD; bf16_t* E2T = ET;
;     bf16_t* KKtT = (bf16_t*)(shm + 73728); bf16_t* VmT = KKtT + 64 * LD; bf16_t* KpT = VmT + 64 * LD; bf16_t* BpT = KpT + 64 * LD;
;     bf16_t* YVt = KpT; bf16_t* W1t = BpT; bf16_t* U0t = VmT;
;     bf16_t* Aak = (bf16_t*)(shm + 110592); bf16_t* Aqk = Aak + 64 * LD;
;     float* red = (float*)Aak; float* tot = red + 256;
;     bf16_t* w2P = (bf16_t*)(shm + 131072); bf16_t* a2P = w2P + 64 * LD;
;     float* prm = (float*)(shm + 131072 + 18432);
;     {
;         const int tid0 = threadIdx.x, hh = blockIdx.x & 15;
; #pragma unroll
;         for (int i = 0; i < 4; ++i) { const int pc = tid0 + 512 * i, mat = pc >> 10, ii = (pc >> 4) & 63, s4 = pc & 15;
;             const f32x4 w = *(const f32x4*)((mat ? p.a2 : p.w2) + (size_t)ii * 1024 + hh * 64 + 4 * s4); bf16_t* d = (mat ? a2P : w2P) + (4 * s4) * LD + ii;
;             d[0] = f2bf(w[0]); d[LD] = f2bf(w[1]); d[2 * LD] = f2bf(w[2]); d[3 * LD] = f2bf(w[3]); }
;         if (tid0 < 64) { const int c = hh * 64 + tid0;
;             prm[tid0] = p.w0[c]; prm[64 + tid0] = p.a0[c]; prm[128 + tid0] = p.mu[c]; prm[192 + tid0] = p.mu[1024 + c]; prm[256 + tid0] = p.mu[2048 + c];
;             prm[320 + tid0] = p.k_k[c]; prm[384 + tid0] = p.k_a[c]; prm[448 + tid0] = p.r_k[c]; prm[512 + tid0] = p.mu[3072 + tid0]; prm[576 + tid0] = p.mu[3136 + tid0]; }
;     }
;     u32x4 zpre[6]; int zcol[6], zrow[6], zlds[6];
;     {
;         const int t0 = threadIdx.x, hh0 = blockIdx.x & 15;
; #pragma unroll
;         for (int i = 0; i < 6; ++i) { int pc = t0 + 512 * i; const bool ok = pc < 2600; pc = ok ? pc : 2599;
;             const bool isH = pc < 1040; const int q = isH ? pc : pc - 1040, r = isH ? q >> 4 : q / 24, rem = isH ? q & 15 : q % 24;
.LBB0_176:
	v_and_b32_e32 v31, 0xc0, v31
	s_movk_i32 s2, 0xc8
	s_mov_b32 s41, 0
	v_mad_u32_u24 v31, v175, s2, v31
	s_mov_b32 s42, s41
	s_mov_b32 s43, s41
	v_add_lshl_u32 v29, v31, v29, 1
	s_mov_b32 s26, s40
	v_add_u32_e32 v31, 0, v135
	s_mov_b32 s40, s41
	v_mov_b64_e32 v[194:195], s[42:43]
	v_cmp_lt_u32_e64 s[8:9], 15, v133
	v_mov_b32_e32 v127, 0
	v_cmp_lt_i32_e64 s[10:11], -1, v156
	v_cmp_ne_u32_e64 s[12:13], 0, v121
	v_cmp_lt_i32_e64 s[14:15], -1, v173
	v_cmp_lt_i32_e64 s[16:17], -1, v172
	v_add_u32_e32 v177, v31, v27
	v_add_u32_e32 v178, 0, v25
	v_add_u32_e32 v179, 0, v29
	s_movk_i32 s3, 0x3a00
	s_movk_i32 s49, 0x1000
	v_lshlrev_b32_e32 v136, 1, v24
	v_lshlrev_b32_e32 v138, 1, v28
	v_lshlrev_b32_e32 v140, 1, v30
	v_lshlrev_b32_e32 v142, 1, v26
	s_movk_i32 s50, 0x90
	s_mov_b32 s2, 0x4038aa3b
	s_movk_i32 s51, 0x190
	s_add_i32 s52, 0, 0x24c00
	s_mov_b32 s4, 0xbfb8aa3b
	s_mov_b32 s6, 0xbf60028c
	v_mbcnt_hi_u32_b32 v180, -1, v129
	s_mov_b32 s53, 0xf800000
	v_mov_b32_e32 v181, 0x260
	s_movk_i32 s54, 0x48
	s_add_i32 s55, 0, 0x12000
	s_add_i32 s56, 0, 0x14400
	s_add_i32 s57, 0, 0x16800
	s_add_i32 s58, 0, 0x18c00
	s_movk_i32 s59, 0x400
	s_movk_i32 s60, 0x200
	s_add_i32 s61, 0, 0x9000
	s_movk_i32 s62, 0x23f
	s_mov_b32 s63, 0xfc00
	s_mov_b32 s64, 0xd800
	s_add_i32 s65, 0, 0x1d400
	s_add_i32 s66, 0, 0x25200
	v_mov_b64_e32 v[192:193], s[40:41]
	s_add_i32 s67, 0, 0x27600
	s_movk_i32 s68, 0x240
	s_movk_i32 s69, 0x50
	v_mov_b32_e32 v182, 0x110
	v_mov_b32_e32 v183, 0xe8
	v_mov_b32_e32 v184, 0x500
	s_load_dwordx2 s[78:79], s[0:1], 0x108
	s_load_dwordx2 s[86:87], s[0:1], 0x118
	s_load_dwordx2 s[88:89], s[0:1], 0xb8
	s_load_dwordx2 s[90:91], s[0:1], 0xe0
	s_load_dwordx2 s[92:93], s[0:1], 0x128
	s_load_dwordx2 s[94:95], s[0:1], 0x130
	s_load_dwordx2 s[96:97], s[0:1], 0xf0
	s_load_dwordx2 s[98:99], s[0:1], 0xf8
	s_load_dwordx2 s[100:101], s[0:1], 0x120
	s_waitcnt vmcnt(0) lgkmcnt(0)
	s_branch .LBB0_178
.LBB0_177:
	s_waitcnt lgkmcnt(0)
	s_barrier
	s_mov_b64 s[20:21], s[78:79]
	s_mov_b64 s[22:23], s[86:87]
	v_add3_u32 v27, s58, v26, v144
	v_mov_b32_e32 v145, v127
	v_add3_u32 v26, s56, v26, v144
	s_waitcnt lgkmcnt(0)
	s_add_u32 s20, s20, s18
	s_addc_u32 s21, s21, s19
	v_lshl_add_u64 v[32:33], s[20:21], 0, v[24:25]
	ds_read_b128 v[28:31], v27
	v_lshl_add_u64 v[36:37], v[32:33], 0, v[144:145]
	ds_read_b128 v[32:35], v26
	s_add_u32 s18, s22, s18
	s_addc_u32 s19, s23, s19
	v_lshl_add_u64 v[24:25], s[18:19], 0, v[24:25]
	v_lshl_add_u64 v[24:25], v[24:25], 0, v[144:145]
	s_andn2_b64 vcc, exec, s[42:43]
	s_mov_b32 s26, s70
	s_waitcnt lgkmcnt(1)
	global_store_dwordx4 v[36:37], v[28:31], off
	s_waitcnt lgkmcnt(0)
	global_store_dwordx4 v[24:25], v[32:35], off
	s_cbranch_vccz .LBB0_279

; __device__ __forceinline__ void phase_prep(const Params& p, unsigned char* shm) {
;     ...
;     auto zload = [&](int it) {
;         const int rw0 = (it >> 4) * 64;
; #pragma unroll
;         for (int i = 0; i < 6; ++i) { int grow = rw0 - 1 + zrow[i]; grow = grow < 0 ? 0 : grow; zpre[i] = *(const u32x4*)(p.Z + (size_t)grow * LDZ + ZC_S + zcol[i]); }
;     };
;     if ((int)blockIdx.x < NCH * 16) zload(blockIdx.x);
;     for (int item = blockIdx.x; item < NCH * 16; item += gridDim.x) {
;         int tid = threadIdx.x; asm volatile("" : "+v"(tid));
;         const int lane = tid & 63, wid = __builtin_amdgcn_readfirstlane(tid >> 6), fr = lane & 15, fq = lane >> 4;
;         const int h = item & 15, cidx = item >> 4, row0 = cidx * 64; const size_t chbase = (size_t)item * 4096;
;         const int crow = tid >> 3, cseg = (tid & 7) * 8;
;         {
;             const bool first = seq_first(row0);
; #pragma unroll
;             for (int i = 0; i < 6; ++i) {
;                 if (zlds[i] >= 0) {
;                     u32x4 v = zpre[i];
;                     if ((i == 0 || i == 2) && first && zrow[i] == 0) { v = (u32x4){0u, 0u, 0u, 0u};
;                         if (row0 >= MP) { const float* sp = p.st_shift + (size_t)((row0 - MP) >> 6) * NSHIFT + zcol[i]; const f32x4 a = *(const f32x4*)sp, b = *(const f32x4*)(sp + 4);
;                             v = (u32x4){pk_bf16(a[0], a[1]), pk_bf16(a[2], a[3]), pk_bf16(b[0], b[1]), pk_bf16(b[2], b[3])}; } }
;                     *(u32x4*)(shm + zlds[i]) = v; } }
;             const int nitem = item + (int)gridDim.x;
;             zload(nitem < NCH * 16 ? nitem : item);
;         }
;         LDS_BARRIER();
;         {
;             const int j = tid >> 3, p8 = tid & 7;
; #pragma unroll
;             for (int isa = 0; isa < 2; ++isa) {
;                 const int c = isa * 64 + 8 * p8;
;                 const u32x4 cu = *(const u32x4*)(zh + (j + 1) * LZH + c), pu = *(const u32x4*)(zh + j * LZH + c);
;                 const f32x4 m0 = *(const f32x4*)(prm + 512 + c), m1 = *(const f32x4*)(prm + 512 + c + 4);
;                 const unsigned cw[4] = {cu.x, cu.y, cu.z, cu.w}, pw[4] = {pu.x, pu.y, pu.z, pu.w};
;                 float x[8];
; #pragma unroll
;                 for (int e = 0; e < 4; ++e) { const float c0 = bf_lo(cw[e]), c1 = bf_hi(cw[e]), mA = e < 2 ? m0[2 * e] : m1[2 * e - 4], mB = e < 2 ? m0[2 * e + 1] : m1[2 * e - 3];
.LBB0_189:
	s_or_b64 exec, exec, s[18:19]
	s_add_i32 s70, s26, s38
	s_cmpk_gt_i32 s70, 0x21ff
	s_cselect_b64 s[42:43], -1, 0
	s_cmpk_lt_i32 s70, 0x2200
	s_cselect_b32 s18, s70, s26
	s_mov_b64 s[20:21], s[88:89]
	s_lshl_b32 s18, s18, 2
	s_andn2_b32 s18, s18, 63
	s_add_i32 s22, s18, -1
	v_add_u32_e32 v0, s22, v123
	v_max_i32_e32 v0, 0, v0
	s_mov_b64 s[18:19], s[90:91]
	s_waitcnt vmcnt(6) lgkmcnt(0)
	v_mov_b64_e32 v[8:9], s[20:21]
	v_mad_u64_u32 v[0:1], s[20:21], v0, s3, v[8:9]
	v_lshlrev_b32_e32 v126, 1, v122
	v_add_u32_e32 v2, s22, v176
	v_lshl_add_u64 v[0:1], v[0:1], 0, v[126:127]
	v_max_i32_e32 v2, 0, v2
	v_add_co_u32_e32 v0, vcc, s49, v0
	v_mad_u64_u32 v[2:3], s[20:21], v2, s3, v[8:9]
	v_mov_b32_e32 v137, v127
	v_addc_co_u32_e32 v1, vcc, 0, v1, vcc
	v_lshl_add_u64 v[2:3], v[2:3], 0, v[136:137]
	v_add_co_u32_e32 v2, vcc, s49, v2
	v_mov_b32_e32 v139, v127
	s_nop 0
	v_addc_co_u32_e32 v3, vcc, 0, v3, vcc
	global_load_dwordx4 v[20:23], v[0:1], off offset:2048
	global_load_dwordx4 v[16:19], v[2:3], off offset:2048
	v_add_u32_e32 v0, s22, v121
	v_max_i32_e32 v0, 0, v0
	v_mad_u64_u32 v[0:1], s[20:21], v0, s3, v[8:9]
	v_add_u32_e32 v2, s22, v175
	v_lshl_add_u64 v[0:1], v[124:125], 1, v[0:1]
	v_max_i32_e32 v2, 0, v2
	v_add_co_u32_e32 v0, vcc, s49, v0
	v_mad_u64_u32 v[2:3], s[20:21], v2, s3, v[8:9]
	v_add_u32_sdwa v10, s22, v157 dst_sel:DWORD dst_unused:UNUSED_PAD src0_sel:DWORD src1_sel:WORD_1
	v_addc_co_u32_e32 v1, vcc, 0, v1, vcc
	v_lshl_add_u64 v[2:3], v[2:3], 0, v[138:139]
	v_max_i32_e32 v10, 0, v10
	v_add_co_u32_e32 v2, vcc, s49, v2
	v_mad_u64_u32 v[10:11], s[20:21], v10, s3, v[8:9]
	v_mov_b32_e32 v141, v127
	v_add_u32_sdwa v12, s22, v174 dst_sel:DWORD dst_unused:UNUSED_PAD src0_sel:DWORD src1_sel:WORD_1
	v_addc_co_u32_e32 v3, vcc, 0, v3, vcc
	v_lshl_add_u64 v[10:11], v[10:11], 0, v[140:141]
	v_max_i32_e32 v12, 0, v12
	v_add_co_u32_e32 v10, vcc, s49, v10
	v_mad_u64_u32 v[8:9], s[20:21], v12, s3, v[8:9]
	v_mov_b32_e32 v143, v127
	v_lshlrev_b32_e32 v188, 3, v187
	v_addc_co_u32_e32 v11, vcc, 0, v11, vcc
	v_lshl_add_u64 v[8:9], v[8:9], 0, v[142:143]
	v_ashrrev_i32_e32 v186, 3, v187
	v_and_b32_e32 v32, 56, v188
	v_add_co_u32_e32 v8, vcc, s49, v8
	v_mul_lo_u32 v24, v186, s48
	s_nop 0
	v_addc_co_u32_e32 v9, vcc, 0, v9, vcc
	v_lshlrev_b32_e32 v144, 1, v32
	global_load_dwordx4 v[4:7], v[0:1], off offset:2048
	s_nop 0
	global_load_dwordx4 v[0:3], v[2:3], off offset:2048
	s_nop 0
	global_load_dwordx4 v[12:15], v[10:11], off offset:2048
	s_nop 0
	global_load_dwordx4 v[8:11], v[8:9], off offset:2048
	s_waitcnt lgkmcnt(0)
	s_barrier
	v_add3_u32 v45, 0, v24, v144
	ds_read_b128 v[24:27], v45 offset:37136
	ds_read_b128 v[28:31], v45 offset:36864
	v_lshlrev_b32_e32 v46, 2, v32
	v_add_u32_e32 v32, 0, v46
	v_add_u32_e32 v47, 0x25000, v32
	ds_read_b128 v[32:35], v47
	ds_read_b128 v[36:39], v47 offset:16
	s_waitcnt lgkmcnt(3)
	v_lshlrev_b32_e32 v40, 16, v24
	v_and_b32_e32 v41, 0xffff0000, v24
	s_waitcnt lgkmcnt(2)
	v_lshlrev_b32_e32 v42, 16, v28
	v_and_b32_e32 v43, 0xffff0000, v28
	v_lshlrev_b32_e32 v24, 16, v25
	v_and_b32_e32 v25, 0xffff0000, v25
	v_lshlrev_b32_e32 v28, 16, v29
	v_and_b32_e32 v29, 0xffff0000, v29
	v_pk_add_f32 v[28:29], v[28:29], v[24:25] neg_lo:[0,1] neg_hi:[0,1]
	v_pk_add_f32 v[42:43], v[42:43], v[40:41] neg_lo:[0,1] neg_hi:[0,1]
	s_waitcnt lgkmcnt(1)
	v_pk_fma_f32 v[24:25], v[34:35], v[28:29], v[24:25]
	v_lshlrev_b32_e32 v28, 16, v26
	v_and_b32_e32 v29, 0xffff0000, v26
	v_lshlrev_b32_e32 v34, 16, v30
	v_and_b32_e32 v35, 0xffff0000, v30
	v_lshlrev_b32_e32 v26, 16, v27
	v_and_b32_e32 v27, 0xffff0000, v27
	v_lshlrev_b32_e32 v30, 16, v31
	v_and_b32_e32 v31, 0xffff0000, v31
	v_pk_add_f32 v[34:35], v[34:35], v[28:29] neg_lo:[0,1] neg_hi:[0,1]
	v_pk_add_f32 v[30:31], v[30:31], v[26:27] neg_lo:[0,1] neg_hi:[0,1]
	v_pk_fma_f32 v[32:33], v[32:33], v[42:43], v[40:41]
	s_waitcnt lgkmcnt(0)
	v_pk_fma_f32 v[28:29], v[36:37], v[34:35], v[28:29]
	v_pk_fma_f32 v[26:27], v[38:39], v[30:31], v[26:27]
	v_pk_mul_f32 v[32:33], v[32:33], s[2:3] op_sel_hi:[1,0]
	v_pk_mul_f32 v[24:25], v[24:25], s[2:3] op_sel_hi:[1,0]
	v_pk_mul_f32 v[28:29], v[28:29], s[2:3] op_sel_hi:[1,0]
	v_pk_mul_f32 v[26:27], v[26:27], s[2:3] op_sel_hi:[1,0]
	v_exp_f32_e32 v32, v32
	v_exp_f32_e32 v33, v33
	v_exp_f32_e32 v24, v24
	v_exp_f32_e32 v25, v25
	v_exp_f32_e32 v28, v28
	v_exp_f32_e32 v29, v29
	v_exp_f32_e32 v26, v26
	v_exp_f32_e32 v27, v27
	v_pk_add_f32 v[32:33], v[32:33], 1.0 op_sel_hi:[1,0]
	v_pk_add_f32 v[24:25], v[24:25], 1.0 op_sel_hi:[1,0]
	v_pk_add_f32 v[28:29], v[28:29], 1.0 op_sel_hi:[1,0]
	v_pk_add_f32 v[26:27], v[26:27], 1.0 op_sel_hi:[1,0]
	v_rcp_f32_e32 v32, v32
	v_rcp_f32_e32 v33, v33
	v_rcp_f32_e32 v24, v24
	v_rcp_f32_e32 v25, v25
	v_rcp_f32_e32 v28, v28
	v_rcp_f32_e32 v29, v29
	v_rcp_f32_e32 v26, v26
	v_rcp_f32_e32 v27, v27
	v_mul_lo_u32 v44, v186, s50
	v_pk_fma_f32 v[30:31], v[32:33], 2.0, 1.0 op_sel_hi:[1,0,0] neg_lo:[1,0,0] neg_hi:[1,0,0]
	v_pk_fma_f32 v[32:33], v[24:25], 2.0, 1.0 op_sel_hi:[1,0,0] neg_lo:[1,0,0] neg_hi:[1,0,0]
	v_pk_fma_f32 v[28:29], v[28:29], 2.0, 1.0 op_sel_hi:[1,0,0] neg_lo:[1,0,0] neg_hi:[1,0,0]
	v_pk_fma_f32 v[34:35], v[26:27], 2.0, 1.0 op_sel_hi:[1,0,0] neg_lo:[1,0,0] neg_hi:[1,0,0]
	v_cvt_pk_bf16_f32 v24, v30, v31
	v_cvt_pk_bf16_f32 v25, v32, v33
	v_cvt_pk_bf16_f32 v26, v28, v29
	v_cvt_pk_bf16_f32 v27, v34, v35
	v_add3_u32 v44, 0, v44, v144
	ds_read_b128 v[28:31], v45 offset:37264
	ds_write_b128 v44, v[24:27]
	ds_read_b128 v[24:27], v45 offset:36992
	ds_read_b128 v[32:35], v47 offset:256
	ds_read_b128 v[36:39], v47 offset:272
	s_and_b32 s22, s26, 15
	s_lshl_b32 s40, s22, 7
	s_waitcnt lgkmcnt(4)
	v_lshlrev_b32_e32 v40, 16, v28
	v_and_b32_e32 v41, 0xffff0000, v28
	s_waitcnt lgkmcnt(2)
; __device__ __forceinline__ unsigned pk_bf16(float lo, float hi) { const f32x2 v = (f32x2){lo, hi}; const bf16v2 b = __builtin_convertvector(v, bf16v2); return __builtin_bit_cast(unsigned, b); }
; __device__ __forceinline__ float bf_lo(unsigned u) { return __uint_as_float(u << 16); }
; __device__ __forceinline__ void phase_prep(const Params& p, unsigned char* shm) {
;     ...
;                 *(u32x4*)((isa ? tha : thw) + j * LD + 8 * p8) = (u32x4){pk_bf16(x[0], x[1]), pk_bf16(x[2], x[3]), pk_bf16(x[4], x[5]), pk_bf16(x[6], x[7])};
;             }
;             {
;                 const u32x4 cu = *(const u32x4*)(zs + (j + 1) * LZS + 128 + 8 * p8), pu = *(const u32x4*)(zs + j * LZS + 128 + 8 * p8);
;                 const f32x4 m0 = *(const f32x4*)(prm + 256 + 8 * p8), m1 = *(const f32x4*)(prm + 256 + 8 * p8 + 4);
;                 const unsigned cw[4] = {cu.x, cu.y, cu.z, cu.w}, pw[4] = {pu.x, pu.y, pu.z, pu.w};
;                 float x[8];
; #pragma unroll
;                 for (int e = 0; e < 4; ++e) { const float c0 = bf_lo(cw[e]), c1 = bf_hi(cw[e]), mA = e < 2 ? m0[2 * e] : m1[2 * e - 4], mB = e < 2 ? m0[2 * e + 1] : m1[2 * e - 3];
;                     x[2 * e] = c0 + mA * (bf_lo(pw[e]) - c0); x[2 * e + 1] = c1 + mB * (bf_hi(pw[e]) - c1); }
;                 *(u32x4*)(p.PV + ((size_t)(row0 + j) * 16 + h) * 64 + 8 * p8) = (u32x4){pk_bf16(x[0], x[1]), pk_bf16(x[2], x[3]), pk_bf16(x[4], x[5]), pk_bf16(x[6], x[7])};
;             }
;         }
;         LDS_BARRIER();
;         const int tt = wid & 3, chh = wid >> 2, tk = 16 * tt + fr, row = row0 + tk;
;         f32x4 lw[2], av[2], vm[2], kkv[2], kp[2], rm[2], cs[2]; float nrm = 0.f, rk = 0.f;
;         {
;             f32x4 accd[2], acca[2];
; #pragma unroll
;             for (int n = 0; n < 2; ++n) { accd[n] = (f32x4){0.f, 0.f, 0.f, 0.f}; acca[n] = (f32x4){0.f, 0.f, 0.f, 0.f}; }
; #pragma unroll
;             for (int ks = 0; ks < 2; ++ks) {
;                 const bf16x8 bw = ldfrag(thw, LD, 16 * tt, 32 * ks, fr, fq), ba = ldfrag(tha, LD, 16 * tt, 32 * ks, fr, fq);
; #pragma unroll
;                 for (int n = 0; n < 2; ++n) {
;                     accd[n] = MFMA16(ldfrag(w2P, LD, 32 * chh + 16 * n, 32 * ks, fr, fq), bw, accd[n]);
;                     acca[n] = MFMA16(ldfrag(a2P, LD, 32 * chh + 16 * n, 32 * ks, fr, fq), ba, acca[n]);
;                 }
;             }
	v_lshlrev_b32_e32 v42, 16, v24
	v_and_b32_e32 v43, 0xffff0000, v24
	v_lshlrev_b32_e32 v28, 16, v29
	v_and_b32_e32 v29, 0xffff0000, v29
	v_lshlrev_b32_e32 v24, 16, v25
	v_and_b32_e32 v25, 0xffff0000, v25
	v_pk_add_f32 v[24:25], v[24:25], v[28:29] neg_lo:[0,1] neg_hi:[0,1]
	v_pk_add_f32 v[42:43], v[42:43], v[40:41] neg_lo:[0,1] neg_hi:[0,1]
	s_waitcnt lgkmcnt(1)
	v_pk_fma_f32 v[28:29], v[34:35], v[24:25], v[28:29]
	v_lshlrev_b32_e32 v24, 16, v30
	v_and_b32_e32 v25, 0xffff0000, v30
	v_lshlrev_b32_e32 v34, 16, v26
	v_and_b32_e32 v35, 0xffff0000, v26
	v_pk_add_f32 v[34:35], v[34:35], v[24:25] neg_lo:[0,1] neg_hi:[0,1]
	v_lshlrev_b32_e32 v26, 16, v27
	s_waitcnt lgkmcnt(0)
	v_pk_fma_f32 v[34:35], v[36:37], v[34:35], v[24:25]
	v_lshlrev_b32_e32 v24, 16, v31
	v_and_b32_e32 v25, 0xffff0000, v31
	v_and_b32_e32 v27, 0xffff0000, v27
	v_pk_add_f32 v[26:27], v[26:27], v[24:25] neg_lo:[0,1] neg_hi:[0,1]
	v_pk_fma_f32 v[32:33], v[32:33], v[42:43], v[40:41]
	v_pk_fma_f32 v[30:31], v[38:39], v[26:27], v[24:25]
	v_cvt_pk_bf16_f32 v24, v32, v33
	v_cvt_pk_bf16_f32 v25, v28, v29
	v_cvt_pk_bf16_f32 v26, v34, v35
	v_cvt_pk_bf16_f32 v27, v30, v31
	ds_write_b128 v44, v[24:27] offset:9216
	v_mul_lo_u32 v24, v186, s51
	v_add3_u32 v28, 0, v24, v144
	ds_read_b128 v[24:27], v28 offset:55200
	ds_read_b128 v[28:31], v28 offset:54800
	v_add_u32_e32 v36, s52, v46
	ds_read_b128 v[32:35], v36
	ds_read_b128 v[36:39], v36 offset:16
	v_mov_b32_e32 v145, v127
	s_waitcnt lgkmcnt(3)
	v_lshlrev_b32_e32 v40, 16, v24
	v_and_b32_e32 v41, 0xffff0000, v24
	s_waitcnt lgkmcnt(2)
	v_lshlrev_b32_e32 v42, 16, v28
	v_and_b32_e32 v43, 0xffff0000, v28
	v_lshlrev_b32_e32 v24, 16, v25
	v_and_b32_e32 v25, 0xffff0000, v25
	v_lshlrev_b32_e32 v28, 16, v29
	v_and_b32_e32 v29, 0xffff0000, v29
	v_pk_add_f32 v[28:29], v[28:29], v[24:25] neg_lo:[0,1] neg_hi:[0,1]
	v_pk_add_f32 v[42:43], v[42:43], v[40:41] neg_lo:[0,1] neg_hi:[0,1]
	s_waitcnt lgkmcnt(1)
	v_pk_fma_f32 v[28:29], v[34:35], v[28:29], v[24:25]
	v_lshlrev_b32_e32 v24, 16, v26
	v_and_b32_e32 v25, 0xffff0000, v26
	v_lshlrev_b32_e32 v34, 16, v30
	v_and_b32_e32 v35, 0xffff0000, v30
	v_pk_add_f32 v[34:35], v[34:35], v[24:25] neg_lo:[0,1] neg_hi:[0,1]
	v_lshlrev_b32_e32 v26, 16, v31
	s_waitcnt lgkmcnt(0)
	v_pk_fma_f32 v[34:35], v[36:37], v[34:35], v[24:25]
	v_lshlrev_b32_e32 v24, 16, v27
	v_and_b32_e32 v25, 0xffff0000, v27
	v_and_b32_e32 v27, 0xffff0000, v31
	v_pk_add_f32 v[26:27], v[26:27], v[24:25] neg_lo:[0,1] neg_hi:[0,1]
	v_pk_fma_f32 v[32:33], v[32:33], v[42:43], v[40:41]
	v_pk_fma_f32 v[30:31], v[38:39], v[26:27], v[24:25]
	v_cvt_pk_bf16_f32 v25, v28, v29
	v_add_u32_e32 v28, s24, v186
	v_ashrrev_i32_e32 v29, 31, v28
	v_lshlrev_b64 v[28:29], 11, v[28:29]
	v_lshl_add_u64 v[28:29], s[18:19], 0, v[28:29]
	v_lshl_add_u64 v[28:29], v[28:29], 0, s[40:41]
	s_ashr_i32 s29, s25, 8
	v_and_b32_e32 v185, 15, v187
	v_cvt_pk_bf16_f32 v24, v32, v33
	v_cvt_pk_bf16_f32 v26, v34, v35
	v_cvt_pk_bf16_f32 v27, v30, v31
	v_lshl_add_u64 v[28:29], v[28:29], 0, v[144:145]
	s_lshl_b32 s18, s29, 5
	global_store_dwordx4 v[28:29], v[24:27], off
	v_and_b32_e32 v141, 48, v187
	s_waitcnt lgkmcnt(0)
	s_barrier
	v_or_b32_e32 v24, s18, v185
	v_mul_lo_u32 v145, v24, s50
	v_add3_u32 v60, s5, v141, v145
	s_bfe_u32 s28, s25, 0x20006
	ds_read_b128 v[24:27], v60
	v_lshl_or_b32 v126, s28, 4, v185
	v_mad_u32_u24 v143, v126, s50, 0
	v_add_u32_e32 v189, v143, v141
	v_add3_u32 v64, s7, v141, v145
	ds_read_b128 v[28:31], v189
	ds_read_b128 v[32:35], v64
	ds_read_b128 v[36:39], v189 offset:64
	ds_read_b128 v[40:43], v60 offset:64
	ds_read_b128 v[44:47], v189 offset:9216
	ds_read_b128 v[48:51], v189 offset:9280
	ds_read_b128 v[52:55], v64 offset:64
	ds_read_b128 v[56:59], v60 offset:2304
	ds_read_b128 v[60:63], v60 offset:2368
	s_waitcnt lgkmcnt(4)
	v_mfma_f32_16x16x32_bf16 v[32:35], v[32:35], v[44:47], 0
	v_bfe_u32 v137, v187, 4, 2
	v_lshlrev_b32_e32 v139, 2, v137
	v_or_b32_e32 v146, s18, v139
	v_mfma_f32_16x16x32_bf16 v[24:27], v[24:27], v[28:31], 0
	v_lshlrev_b32_e32 v147, 1, v146
	s_lshl_b32 s20, s28, 8
	s_add_i32 s20, s20, 0
	s_waitcnt lgkmcnt(1)
	v_mfma_f32_16x16x32_bf16 v[28:31], v[56:59], v[28:31], 0
	ds_read_b128 v[56:59], v64 offset:2304
	ds_read_b128 v[64:67], v64 offset:2368
	s_add_i32 s20, s20, 0x1b400
	v_cmp_eq_u32_e64 s[18:19], 15, v185
	v_mfma_f32_16x16x32_bf16 v[72:75], v[52:55], v[48:51], v[32:35]
	v_lshl_add_u32 v191, v146, 2, s20
	s_nop 1
	v_lshlrev_b32_e32 v34, 2, v146
	v_add_u32_e32 v35, 0, v34
	v_mfma_f32_16x16x32_bf16 v[40:43], v[40:43], v[36:39], v[24:27]
	v_add_u32_e32 v32, 0x24900, v35
	ds_read_b128 v[84:87], v32
	s_waitcnt lgkmcnt(3)
	v_mfma_f32_16x16x32_bf16 v[24:27], v[60:63], v[36:39], v[28:31]
	v_lshlrev_b32_e32 v36, 8, v126
	s_nop 1
	v_add_u32_e32 v28, 0x24800, v35
	ds_read_b128 v[28:31], v28
	s_waitcnt lgkmcnt(3)
	v_mfma_f32_16x16x32_bf16 v[44:47], v[56:59], v[44:47], 0
	s_waitcnt lgkmcnt(0)
; __device__ __forceinline__ void phase_prep(const Params& p, unsigned char* shm) {
;     ...
;             const bf16_t* zc = zs + (tk + 1) * LZS; const bf16_t* zp = zs + tk * LZS;
; #pragma unroll
;             for (int n = 0; n < 2; ++n) {
;                 const int c4 = 32 * chh + 16 * n + 4 * fq;
;                 const f32x4 d = *(const f32x4*)(prm + c4) + accd[n], al = *(const f32x4*)(prm + 64 + c4) + acca[n];
; { const f32x2 s0 = sigmoid2((f32x2){d[0], d[1]}), s1 = sigmoid2((f32x2){d[2], d[3]}), a0 = sigmoid2((f32x2){al[0], al[1]}), a1 = sigmoid2((f32x2){al[2], al[3]});
;                   lw[n] = (f32x4){s0.x, s0.y, s1.x, s1.y} * (-0.87503886f); av[n] = (f32x4){a0.x, a0.y, a1.x, a1.y}; }
;                 { const f32x4 vc = ld_bf4(zc + 128 + c4), vp = ld_bf4(zp + 128 + c4); vm[n] = vc + *(const f32x4*)(prm + 256 + c4) * (vp - vc); }
;                 const f32x4 kc = ld_bf4(zc + 64 + c4), kpv = ld_bf4(zp + 64 + c4);
;                 const f32x4 k = kc + *(const f32x4*)(prm + 192 + c4) * (kpv - kc);
;                 kkv[n] = k * *(const f32x4*)(prm + 320 + c4);
;                 kp[n] = k * (1.0f + (av[n] - 1.0f) * *(const f32x4*)(prm + 384 + c4));
;                 const f32x4 rc = ld_bf4(zc + c4), rp = ld_bf4(zp + c4);
;                 rm[n] = rc + *(const f32x4*)(prm + 128 + c4) * (rp - rc);
;                 const f32x4 rkw = rm[n] * kp[n] * *(const f32x4*)(prm + 448 + c4);
;                 { const f32x4 sq = kkv[n] * kkv[n]; nrm += (sq[0] + sq[1]) + (sq[2] + sq[3]); }
;                 rk += rkw[0] + rkw[1] + rkw[2] + rkw[3];
; #pragma unroll
;                 for (int j = 0; j < 4; ++j) {
;                     float x = lw[n][j];
;                     x += __int_as_float(__builtin_amdgcn_update_dpp(0, __float_as_int(x), 0x111, 0xf, 0xf, false));
;                     x += __int_as_float(__builtin_amdgcn_update_dpp(0, __float_as_int(x), 0x112, 0xf, 0xf, false));
;                     x += __int_as_float(__builtin_amdgcn_update_dpp(0, __float_as_int(x), 0x114, 0xf, 0xf, false));
;                     x += __int_as_float(__builtin_amdgcn_update_dpp(0, __float_as_int(x), 0x118, 0xf, 0xf, false));
;                     cs[n][j] = x;
;                 }
;                 if (fr == 15) *(f32x4*)(tot + tt * 64 + c4) = cs[n];
;             }
	v_pk_add_f32 v[28:29], v[40:41], v[28:29]
	s_nop 0
	v_pk_mul_f32 v[28:29], v[28:29], s[4:5] op_sel_hi:[1,0]
	v_pk_add_f32 v[30:31], v[42:43], v[30:31]
	v_exp_f32_e32 v28, v28
	v_exp_f32_e32 v29, v29
	v_mfma_f32_16x16x32_bf16 v[56:59], v[64:67], v[48:51], v[44:47]
	v_mul_f32_e64 v30, v30, s4
	v_mul_f32_e64 v31, v31, s4
	v_pk_add_f32 v[28:29], v[28:29], 1.0 op_sel_hi:[1,0]
	s_nop 0
	v_rcp_f32_e32 v32, v28
	v_rcp_f32_e32 v33, v29
	v_add3_u32 v28, v143, v36, v147
	v_add_u32_e32 v28, 0xd000, v28
	v_add_u32_e32 v29, s52, v34
	v_add_u32_e32 v34, 0x24b00, v35
	ds_read2_b64 v[52:55], v28 offset0:228 offset1:244
	ds_read2_b64 v[48:51], v28 offset0:194 offset1:212
	ds_read2_b64 v[68:71], v28 offset0:162 offset1:178
	ds_read_b128 v[44:47], v29
	ds_read_b128 v[92:95], v34
	v_add_u32_e32 v29, 0x24d00, v35
	v_add_u32_e32 v34, 0x24e00, v35
	v_exp_f32_e32 v30, v30
	v_exp_f32_e32 v31, v31
	ds_read_b128 v[96:99], v29
	ds_read_b128 v[76:79], v34
	v_add_u32_e32 v29, 0x24a00, v35
	v_add_u32_e32 v34, 0x24f00, v35
	v_pk_mul_f32 v[154:155], v[32:33], s[6:7] op_sel_hi:[1,0]
	ds_read_b128 v[64:67], v29
	ds_read_b128 v[60:63], v34
	v_mov_b32_e32 v34, v127
	v_mov_b32_e32 v35, v127
	v_pk_add_f32 v[30:31], v[30:31], 1.0 op_sel_hi:[1,0]
	v_mov_b32_dpp v34, v154 row_shr:1 row_mask:0xf bank_mask:0xf
	v_mov_b32_dpp v35, v155 row_shr:1 row_mask:0xf bank_mask:0xf
	v_pk_fma_f32 v[32:33], v[32:33], s[6:7], v[34:35] op_sel_hi:[1,0,1]
	v_mov_b32_e32 v34, v127
	v_mov_b32_e32 v35, v127
	v_rcp_f32_e32 v30, v30
	v_mov_b32_dpp v34, v32 row_shr:2 row_mask:0xf bank_mask:0xf
	v_mov_b32_dpp v35, v33 row_shr:2 row_mask:0xf bank_mask:0xf
	v_rcp_f32_e32 v31, v31
	v_pk_add_f32 v[32:33], v[32:33], v[34:35]
	v_mov_b32_e32 v34, v127
	v_mov_b32_e32 v35, v127
	v_pk_mul_f32 v[152:153], v[30:31], s[6:7] op_sel_hi:[1,0]
	v_mov_b32_dpp v34, v32 row_shr:4 row_mask:0xf bank_mask:0xf
	v_mov_b32_dpp v35, v33 row_shr:4 row_mask:0xf bank_mask:0xf
	v_pk_add_f32 v[32:33], v[32:33], v[34:35]
	v_mov_b32_e32 v34, v127
	v_mov_b32_e32 v35, v127
	s_nop 0
	v_mov_b32_dpp v34, v32 row_shr:8 row_mask:0xf bank_mask:0xf
	v_mov_b32_dpp v35, v33 row_shr:8 row_mask:0xf bank_mask:0xf
	v_pk_add_f32 v[40:41], v[32:33], v[34:35]
	v_mov_b32_e32 v32, v127
	v_mov_b32_e32 v33, v127
	s_nop 0
	v_mov_b32_dpp v32, v152 row_shr:1 row_mask:0xf bank_mask:0xf
	v_mov_b32_dpp v33, v153 row_shr:1 row_mask:0xf bank_mask:0xf
	v_pk_fma_f32 v[30:31], v[30:31], s[6:7], v[32:33] op_sel_hi:[1,0,1]
	v_mov_b32_e32 v32, v127
	v_mov_b32_e32 v33, v127
	s_nop 0
	v_mov_b32_dpp v32, v30 row_shr:2 row_mask:0xf bank_mask:0xf
	v_mov_b32_dpp v33, v31 row_shr:2 row_mask:0xf bank_mask:0xf
	v_pk_add_f32 v[30:31], v[30:31], v[32:33]
	v_mov_b32_e32 v32, v127
	v_mov_b32_e32 v33, v127
	s_nop 0
	v_mov_b32_dpp v32, v30 row_shr:4 row_mask:0xf bank_mask:0xf
	v_mov_b32_dpp v33, v31 row_shr:4 row_mask:0xf bank_mask:0xf
	v_pk_add_f32 v[30:31], v[30:31], v[32:33]
	v_mov_b32_e32 v32, v127
	v_mov_b32_e32 v33, v127
	s_nop 0
	v_mov_b32_dpp v32, v30 row_shr:8 row_mask:0xf bank_mask:0xf
	v_mov_b32_dpp v33, v31 row_shr:8 row_mask:0xf bank_mask:0xf
	v_pk_add_f32 v[42:43], v[30:31], v[32:33]
	s_and_saveexec_b64 s[20:21], s[18:19]
	ds_write_b128 v191, v[40:43]
	s_or_b64 exec, exec, s[20:21]
	v_or_b32_e32 v29, 16, v146
	v_lshl_add_u32 v190, v29, 2, 0
	v_add_u32_e32 v29, 0x24800, v190
	ds_read_b128 v[30:33], v29
	v_mov_b32_e32 v196, v127
	v_mov_b32_e32 v197, v127
	v_add_u32_e32 v29, 0x24900, v190
	ds_read_b128 v[116:119], v29
	s_waitcnt lgkmcnt(1)
	v_pk_add_f32 v[24:25], v[24:25], v[30:31]
	v_pk_add_f32 v[26:27], v[26:27], v[32:33]
	v_pk_mul_f32 v[24:25], v[24:25], s[4:5] op_sel_hi:[1,0]
	v_pk_mul_f32 v[26:27], v[26:27], s[4:5] op_sel_hi:[1,0]
	v_exp_f32_e32 v24, v24
	v_exp_f32_e32 v25, v25
	v_exp_f32_e32 v26, v26
	v_exp_f32_e32 v27, v27
	v_add_u32_e32 v29, 0x24c00, v190
	v_pk_add_f32 v[24:25], v[24:25], 1.0 op_sel_hi:[1,0]
	v_add_u32_e32 v80, 0x24b00, v190
	v_rcp_f32_e32 v24, v24
	v_rcp_f32_e32 v25, v25
	v_pk_add_f32 v[26:27], v[26:27], 1.0 op_sel_hi:[1,0]
	ds_read2_b64 v[36:39], v28 offset0:232 offset1:248
	ds_read2_b64 v[32:35], v28 offset0:198 offset1:216
	v_rcp_f32_e32 v26, v26
	v_pk_mul_f32 v[150:151], v[24:25], s[6:7] op_sel_hi:[1,0]
	v_rcp_f32_e32 v27, v27
	ds_read2_b64 v[100:103], v28 offset0:166 offset1:182
	v_mov_b32_dpp v196, v150 row_shr:1 row_mask:0xf bank_mask:0xf
	v_mov_b32_dpp v197, v151 row_shr:1 row_mask:0xf bank_mask:0xf
	v_pk_fma_f32 v[24:25], v[24:25], s[6:7], v[196:197] op_sel_hi:[1,0,1]
	v_mov_b32_e32 v196, v127
	v_mov_b32_e32 v197, v127
	v_pk_mul_f32 v[148:149], v[26:27], s[6:7] op_sel_hi:[1,0]
	v_mov_b32_dpp v196, v24 row_shr:2 row_mask:0xf bank_mask:0xf
	v_mov_b32_dpp v197, v25 row_shr:2 row_mask:0xf bank_mask:0xf
	v_pk_add_f32 v[24:25], v[24:25], v[196:197]
	v_mov_b32_e32 v196, v127
	v_mov_b32_e32 v197, v127
	ds_read_b128 v[28:31], v29
	ds_read_b128 v[108:111], v80
	v_mov_b32_dpp v196, v24 row_shr:4 row_mask:0xf bank_mask:0xf
	v_mov_b32_dpp v197, v25 row_shr:4 row_mask:0xf bank_mask:0xf
	v_pk_add_f32 v[24:25], v[24:25], v[196:197]
	v_mov_b32_e32 v196, v127
	v_mov_b32_e32 v197, v127
	v_add_u32_e32 v80, 0x24d00, v190
	v_mov_b32_dpp v196, v24 row_shr:8 row_mask:0xf bank_mask:0xf
	v_mov_b32_dpp v197, v25 row_shr:8 row_mask:0xf bank_mask:0xf
	v_pk_add_f32 v[24:25], v[24:25], v[196:197]
	v_mov_b32_e32 v196, v127
	v_mov_b32_e32 v197, v127
	v_add_u32_e32 v81, 0x24e00, v190
	v_mov_b32_dpp v196, v148 row_shr:1 row_mask:0xf bank_mask:0xf
	v_mov_b32_dpp v197, v149 row_shr:1 row_mask:0xf bank_mask:0xf
	v_pk_fma_f32 v[26:27], v[26:27], s[6:7], v[196:197] op_sel_hi:[1,0,1]
	v_mov_b32_e32 v196, v127
	v_mov_b32_e32 v197, v127
	ds_read_b128 v[112:115], v80
; __device__ __forceinline__ f32x4 ld_bf4(const bf16_t* p) { const u32x2 u = *(const u32x2*)p; return (f32x4){bf_lo(u.x), bf_hi(u.x), bf_lo(u.y), bf_hi(u.y)}; }
; #define LDS_BARRIER() do { asm volatile("s_waitcnt lgkmcnt(0)" ::: "memory"); __builtin_amdgcn_s_barrier(); asm volatile("" ::: "memory"); } while (0)
; __device__ __forceinline__ void phase_prep(const Params& p, unsigned char* shm) {
;     ...
;                 { const f32x4 vc = ld_bf4(zc + 128 + c4), vp = ld_bf4(zp + 128 + c4); vm[n] = vc + *(const f32x4*)(prm + 256 + c4) * (vp - vc); }
;                 const f32x4 kc = ld_bf4(zc + 64 + c4), kpv = ld_bf4(zp + 64 + c4);
;                 const f32x4 k = kc + *(const f32x4*)(prm + 192 + c4) * (kpv - kc);
;                 kkv[n] = k * *(const f32x4*)(prm + 320 + c4);
;                 kp[n] = k * (1.0f + (av[n] - 1.0f) * *(const f32x4*)(prm + 384 + c4));
;                 const f32x4 rc = ld_bf4(zc + c4), rp = ld_bf4(zp + c4);
;                 rm[n] = rc + *(const f32x4*)(prm + 128 + c4) * (rp - rc);
;                 const f32x4 rkw = rm[n] * kp[n] * *(const f32x4*)(prm + 448 + c4);
;                 { const f32x4 sq = kkv[n] * kkv[n]; nrm += (sq[0] + sq[1]) + (sq[2] + sq[3]); }
;                 rk += rkw[0] + rkw[1] + rkw[2] + rkw[3];
; #pragma unroll
;                 for (int j = 0; j < 4; ++j) {
;                     float x = lw[n][j];
;                     x += __int_as_float(__builtin_amdgcn_update_dpp(0, __float_as_int(x), 0x111, 0xf, 0xf, false));
;                     x += __int_as_float(__builtin_amdgcn_update_dpp(0, __float_as_int(x), 0x112, 0xf, 0xf, false));
;                     x += __int_as_float(__builtin_amdgcn_update_dpp(0, __float_as_int(x), 0x114, 0xf, 0xf, false));
;                     x += __int_as_float(__builtin_amdgcn_update_dpp(0, __float_as_int(x), 0x118, 0xf, 0xf, false));
;                     cs[n][j] = x;
;                 }
;                 if (fr == 15) *(f32x4*)(tot + tt * 64 + c4) = cs[n];
;             }
;             nrm += __shfl_xor(nrm, 16); nrm += __shfl_xor(nrm, 32);
;             rk += __shfl_xor(rk, 16); rk += __shfl_xor(rk, 32);
;             if (fq == 0) { red[wid * 16 + fr] = nrm; red[128 + wid * 16 + fr] = rk; }
;         }
;         LDS_BARRIER();
	ds_read_b128 v[104:107], v81
	v_add_u32_e32 v80, 0x24a00, v190
	v_add_u32_e32 v81, 0x24f00, v190
	v_mov_b32_dpp v196, v26 row_shr:2 row_mask:0xf bank_mask:0xf
	v_mov_b32_dpp v197, v27 row_shr:2 row_mask:0xf bank_mask:0xf
	ds_read_b128 v[88:91], v80
	ds_read_b128 v[80:83], v81
	v_pk_add_f32 v[26:27], v[26:27], v[196:197]
	v_mov_b32_e32 v196, v127
	v_mov_b32_e32 v197, v127
	s_nop 0
	v_mov_b32_dpp v196, v26 row_shr:4 row_mask:0xf bank_mask:0xf
	v_mov_b32_dpp v197, v27 row_shr:4 row_mask:0xf bank_mask:0xf
	v_pk_add_f32 v[26:27], v[26:27], v[196:197]
	v_mov_b32_e32 v196, v127
	v_mov_b32_e32 v197, v127
	s_nop 0
	v_mov_b32_dpp v196, v26 row_shr:8 row_mask:0xf bank_mask:0xf
	v_mov_b32_dpp v197, v27 row_shr:8 row_mask:0xf bank_mask:0xf
	v_pk_add_f32 v[26:27], v[26:27], v[196:197]
	s_and_saveexec_b64 s[20:21], s[18:19]
	ds_write_b128 v191, v[24:27] offset:64
	s_or_b64 exec, exec, s[20:21]
	v_pk_add_f32 v[74:75], v[74:75], v[86:87]
	v_pk_add_f32 v[72:73], v[72:73], v[84:85]
	v_pk_mul_f32 v[74:75], v[74:75], s[4:5] op_sel_hi:[1,0]
	v_pk_mul_f32 v[72:73], v[72:73], s[4:5] op_sel_hi:[1,0]
	v_exp_f32_e32 v74, v74
	v_exp_f32_e32 v75, v75
	v_exp_f32_e32 v72, v72
	v_exp_f32_e32 v73, v73
	v_lshlrev_b32_e32 v84, 16, v52
	v_pk_add_f32 v[74:75], v[74:75], 1.0 op_sel_hi:[1,0]
	v_and_b32_e32 v85, 0xffff0000, v52
	v_pk_add_f32 v[72:73], v[72:73], 1.0 op_sel_hi:[1,0]
	v_rcp_f32_e32 v74, v74
	v_rcp_f32_e32 v75, v75
	v_rcp_f32_e32 v72, v72
	v_rcp_f32_e32 v73, v73
	v_lshlrev_b32_e32 v52, 16, v53
	v_and_b32_e32 v53, 0xffff0000, v53
	v_lshlrev_b32_e32 v86, 16, v70
	v_and_b32_e32 v87, 0xffff0000, v70
	v_lshlrev_b32_e32 v70, 16, v71
	v_and_b32_e32 v71, 0xffff0000, v71
	v_sub_f32_e32 v71, v71, v53
	v_sub_f32_e32 v70, v70, v52
	v_pk_fma_f32 v[52:53], v[94:95], v[70:71], v[52:53]
	v_pk_add_f32 v[94:95], v[74:75], -1.0 op_sel_hi:[1,0]
	v_sub_f32_e32 v87, v87, v85
	v_sub_f32_e32 v86, v86, v84
	v_pk_add_f32 v[70:71], v[72:73], -1.0 op_sel_hi:[1,0]
	v_pk_fma_f32 v[78:79], v[78:79], v[94:95], 1.0 op_sel_hi:[1,1,0]
	v_pk_fma_f32 v[92:93], v[92:93], v[86:87], v[84:85]
	v_pk_mul_f32 v[84:85], v[98:99], v[52:53]
	v_pk_fma_f32 v[70:71], v[76:77], v[70:71], 1.0 op_sel_hi:[1,1,0]
	v_pk_mul_f32 v[76:77], v[52:53], v[78:79]
	v_lshlrev_b32_e32 v52, 16, v50
	v_and_b32_e32 v53, 0xffff0000, v50
	v_lshlrev_b32_e32 v78, 16, v68
	v_and_b32_e32 v68, 0xffff0000, v68
	v_pk_mul_f32 v[86:87], v[96:97], v[92:93]
	v_pk_mul_f32 v[70:71], v[92:93], v[70:71]
	v_lshlrev_b32_e32 v50, 16, v51
	v_and_b32_e32 v51, 0xffff0000, v51
	v_lshlrev_b32_e32 v92, 16, v69
	v_and_b32_e32 v79, 0xffff0000, v69
	v_sub_f32_e32 v69, v68, v53
	v_sub_f32_e32 v68, v78, v52
	v_sub_f32_e32 v79, v79, v51
	v_sub_f32_e32 v78, v92, v50
	v_pk_fma_f32 v[64:65], v[64:65], v[68:69], v[52:53]
	v_pk_fma_f32 v[66:67], v[66:67], v[78:79], v[50:51]
	v_pk_mul_f32 v[50:51], v[70:71], v[64:65]
	v_pk_mul_f32 v[52:53], v[76:77], v[66:67]
	v_pk_mul_f32 v[50:51], v[60:61], v[50:51]
	v_pk_mul_f32 v[52:53], v[62:63], v[52:53]
	v_add_f32_e32 v50, v50, v51
	v_add_f32_e32 v50, v52, v50
	v_add_f32_e32 v50, v53, v50
	v_add_f32_e32 v93, 0, v50
	s_waitcnt lgkmcnt(9)
	v_pk_add_f32 v[50:51], v[58:59], v[118:119]
	v_pk_add_f32 v[52:53], v[56:57], v[116:117]
	v_pk_mul_f32 v[50:51], v[50:51], s[4:5] op_sel_hi:[1,0]
	v_pk_mul_f32 v[52:53], v[52:53], s[4:5] op_sel_hi:[1,0]
	v_exp_f32_e32 v56, v50
	v_exp_f32_e32 v52, v52
	v_exp_f32_e32 v53, v53
	v_exp_f32_e32 v57, v51
	v_pk_mul_f32 v[60:61], v[84:85], v[84:85]
	v_pk_mul_f32 v[62:63], v[86:87], v[86:87]
	v_pk_add_f32 v[50:51], v[52:53], 1.0 op_sel_hi:[1,0]
	v_pk_add_f32 v[52:53], v[56:57], 1.0 op_sel_hi:[1,0]
	v_rcp_f32_e32 v50, v50
	v_rcp_f32_e32 v51, v51
	v_rcp_f32_e32 v52, v52
	v_rcp_f32_e32 v53, v53
	v_add_f32_e32 v62, v62, v63
	v_add_f32_e32 v60, v60, v61
	s_waitcnt lgkmcnt(8)
	v_lshlrev_b32_e32 v56, 16, v36
	v_and_b32_e32 v57, 0xffff0000, v36
	v_lshlrev_b32_e32 v36, 16, v37
	v_and_b32_e32 v37, 0xffff0000, v37
	s_waitcnt lgkmcnt(6)
	v_lshlrev_b32_e32 v58, 16, v103
	v_and_b32_e32 v59, 0xffff0000, v103
	v_add_f32_e32 v92, v62, v60
	v_lshlrev_b32_e32 v60, 16, v102
	v_and_b32_e32 v61, 0xffff0000, v102
	v_sub_f32_e32 v59, v59, v37
	v_sub_f32_e32 v58, v58, v36
	v_sub_f32_e32 v61, v61, v57
	v_sub_f32_e32 v60, v60, v56
	s_waitcnt lgkmcnt(4)
	v_pk_fma_f32 v[62:63], v[110:111], v[58:59], v[36:37]
	v_pk_add_f32 v[36:37], v[50:51], -1.0 op_sel_hi:[1,0]
	v_pk_add_f32 v[68:69], v[52:53], -1.0 op_sel_hi:[1,0]
	v_pk_fma_f32 v[56:57], v[108:109], v[60:61], v[56:57]
	s_waitcnt lgkmcnt(2)
	v_pk_fma_f32 v[68:69], v[106:107], v[68:69], 1.0 op_sel_hi:[1,1,0]
	v_pk_fma_f32 v[36:37], v[104:105], v[36:37], 1.0 op_sel_hi:[1,1,0]
	v_pk_mul_f32 v[58:59], v[114:115], v[62:63]
	v_pk_mul_f32 v[60:61], v[112:113], v[56:57]
	v_pk_mul_f32 v[36:37], v[56:57], v[36:37]
	v_pk_mul_f32 v[56:57], v[62:63], v[68:69]
	v_lshlrev_b32_e32 v62, 16, v34
	v_and_b32_e32 v63, 0xffff0000, v34
	v_lshlrev_b32_e32 v34, 16, v35
	v_and_b32_e32 v35, 0xffff0000, v35
	v_lshlrev_b32_e32 v68, 16, v100
	v_and_b32_e32 v69, 0xffff0000, v100
	v_lshlrev_b32_e32 v78, 16, v101
	v_and_b32_e32 v79, 0xffff0000, v101
	v_sub_f32_e32 v69, v69, v63
	v_sub_f32_e32 v68, v68, v62
	v_sub_f32_e32 v79, v79, v35
	v_sub_f32_e32 v78, v78, v34
	s_waitcnt lgkmcnt(1)
	v_pk_fma_f32 v[34:35], v[90:91], v[78:79], v[34:35]
	v_pk_fma_f32 v[62:63], v[88:89], v[68:69], v[62:63]
	v_pk_mul_f32 v[78:79], v[56:57], v[34:35]
	v_pk_mul_f32 v[68:69], v[36:37], v[62:63]
	s_waitcnt lgkmcnt(0)
	v_pk_mul_f32 v[78:79], v[82:83], v[78:79]
	v_pk_mul_f32 v[68:69], v[80:81], v[68:69]
	v_pk_mul_f32 v[80:81], v[58:59], v[58:59]
	v_pk_mul_f32 v[82:83], v[60:61], v[60:61]
	v_add_f32_e32 v80, v80, v81
	v_add_f32_e32 v82, v82, v83
	v_add_f32_e32 v80, v82, v80
	v_and_b32_e32 v82, 64, v180
	v_xor_b32_e32 v81, 16, v180
	v_add_u32_e32 v82, 64, v82
	v_add_f32_e32 v68, v68, v69
	v_cmp_lt_i32_e32 vcc, v81, v82
	v_add_f32_e32 v68, v78, v68
	v_add_f32_e32 v68, v79, v68
	v_cndmask_b32_e32 v81, v180, v81, vcc
	v_add_f32_e32 v80, v92, v80
	v_lshlrev_b32_e32 v81, 2, v81
	v_add_f32_e32 v68, v93, v68
	ds_bpermute_b32 v83, v81, v80
	ds_bpermute_b32 v79, v81, v68
	v_xor_b32_e32 v78, 32, v180
	v_cmp_lt_i32_e32 vcc, v78, v82
	s_ashr_i32 s71, s25, 6
	s_waitcnt lgkmcnt(1)
	v_add_f32_e32 v69, v80, v83
	v_cndmask_b32_e32 v78, v180, v78, vcc
	v_lshlrev_b32_e32 v78, 2, v78
	s_waitcnt lgkmcnt(0)
	v_add_f32_e32 v79, v68, v79
	ds_bpermute_b32 v80, v78, v69
	ds_bpermute_b32 v81, v78, v79
	v_and_b32_e32 v68, 63, v187
	s_ashr_i32 s27, s26, 31
	v_cmp_gt_u32_e32 vcc, 16, v68
	s_waitcnt lgkmcnt(1)
	v_add_f32_e32 v78, v69, v80
	s_waitcnt lgkmcnt(0)
	v_add_f32_e32 v69, v79, v81
	s_lshl_b32 s72, s71, 4
	s_and_saveexec_b64 s[20:21], vcc
	s_lshl_b32 s23, s72, 2
	s_add_i32 s23, s23, 0
	v_lshl_add_u32 v79, v185, 2, s23
	v_add_u32_e32 v79, 0x1b000, v79
	ds_write2st64_b32 v79, v78, v69 offset1:2
	s_or_b64 exec, exec, s[20:21]
	s_xor_b32 s20, s72, 64
	s_lshl_b32 s20, s20, 2
	s_add_i32 s20, s20, 0
	v_lshl_add_u32 v81, v185, 2, s20
	s_waitcnt lgkmcnt(0)
	s_barrier
; __device__ __forceinline__ void st_bf4(bf16_t* p, f32x4 v) { u32x2 u; u.x = pk_bf16(v[0], v[1]); u.y = pk_bf16(v[2], v[3]); *(u32x2*)p = u; }
; __device__ __forceinline__ void phase_prep(const Params& p, unsigned char* shm) {
;     ...
;         {
;             nrm += red[(wid ^ 4) * 16 + fr]; rk += red[128 + (wid ^ 4) * 16 + fr];
;             const float inv = 1.0f / fmaxf(sqrtf(nrm), 1e-12f);
;             p.PRK[(size_t)row * 16 + h] = rk;
; #pragma unroll
;             for (int n = 0; n < 2; ++n) {
;                 const int c4 = 32 * chh + 16 * n + 4 * fq;
;                 f32x4 pre = (f32x4){0.f, 0.f, 0.f, 0.f}, total = (f32x4){0.f, 0.f, 0.f, 0.f};
; #pragma unroll
;                 for (int t2 = 0; t2 < 4; ++t2) { const f32x4 x = *(const f32x4*)(tot + t2 * 64 + c4); total += x; if (t2 < tt) pre += x; }
;                 const f32x4 csum = pre + cs[n];
;                 f32x4 eg, eng, egm, etc; const f32x4 ncs = -csum, cml = csum - lw[n], tmc = total - csum;
; #pragma unroll
;                 for (int j = 0; j < 4; ++j) { eg[j] = __builtin_amdgcn_exp2f(csum[j]); eng[j] = __builtin_amdgcn_exp2f(ncs[j]); egm[j] = __builtin_amdgcn_exp2f(cml[j]); etc[j] = __builtin_amdgcn_exp2f(tmc[j]); }
;                 const f32x4 kkn = kkv[n] * inv, bb = kkn * av[n];
;                 const f32x4 qt = rm[n] * eg, kt = kp[n] * eng, bt = bb * eng, kkt = kkn * egm, kpp = kp[n] * etc, bpp = bb * etc;
;                 st_bf4(Qt + tk * LD + c4, qt); st_bf4(Kt + tk * LD + c4, kt); st_bf4(Bt + tk * LD + c4, bt);
;                 const u32x2 kkw = pk_bf4(kkt), vmw = pk_bf4(vm[n]), kpw = pk_bf4(kpp), bpw = pk_bf4(bpp);
;                 *(u32x2*)(KKt + tk * LD + c4) = kkw;
;                 { bf16_t* d = KKtT + c4 * LD + tk; d[0] = (bf16_t)kkw.x; d[LD] = (bf16_t)(kkw.x >> 16); d[2 * LD] = (bf16_t)kkw.y; d[3 * LD] = (bf16_t)(kkw.y >> 16); }
;                 { bf16_t* d = VmT + c4 * LD + tk; d[0] = (bf16_t)vmw.x; d[LD] = (bf16_t)(vmw.x >> 16); d[2 * LD] = (bf16_t)vmw.y; d[3 * LD] = (bf16_t)(vmw.y >> 16); }
;                 { bf16_t* d = KpT + c4 * LD + tk; d[0] = (bf16_t)kpw.x; d[LD] = (bf16_t)(kpw.x >> 16); d[2 * LD] = (bf16_t)kpw.y; d[3 * LD] = (bf16_t)(kpw.y >> 16); }
;                 { bf16_t* d = BpT + c4 * LD + tk; d[0] = (bf16_t)bpw.x; d[LD] = (bf16_t)(bpw.x >> 16); d[2 * LD] = (bf16_t)bpw.y; d[3 * LD] = (bf16_t)(bpw.y >> 16); }
	v_add_u32_e32 v81, 0x1b000, v81
	ds_read2st64_b32 v[88:89], v81 offset1:2
	v_and_b32_e32 v83, 0xffff0000, v54
	v_lshlrev_b32_e32 v79, 16, v48
	v_and_b32_e32 v48, 0xffff0000, v48
	v_lshlrev_b32_e32 v81, 16, v49
	v_and_b32_e32 v90, 0xffff0000, v49
	v_sub_f32_e32 v49, v48, v83
	s_waitcnt lgkmcnt(0)
	v_add_f32_e32 v48, v78, v88
	v_mul_f32_e32 v78, 0x4f800000, v48
	v_cmp_gt_f32_e32 vcc, s53, v48
	v_lshlrev_b32_e32 v82, 16, v54
	v_lshlrev_b32_e32 v54, 16, v55
	v_cndmask_b32_e32 v88, v48, v78, vcc
	v_sqrt_f32_e32 v91, v88
	v_and_b32_e32 v55, 0xffff0000, v55
	v_sub_f32_e32 v78, v81, v54
	v_sub_f32_e32 v48, v79, v82
	v_add_u32_e32 v81, -1, v91
	v_sub_f32_e32 v79, v90, v55
	v_fma_f32 v90, -v81, v91, v88
	v_cmp_ge_f32_e64 s[20:21], 0, v90
	v_add_u32_e32 v90, 1, v91
	v_pk_fma_f32 v[82:83], v[44:45], v[48:49], v[82:83]
	v_cndmask_b32_e64 v81, v91, v81, s[20:21]
	v_fma_f32 v91, -v90, v91, v88
	v_cmp_lt_f32_e64 s[20:21], 0, v91
	v_pk_fma_f32 v[54:55], v[46:47], v[78:79], v[54:55]
	v_or_b32_e32 v80, s24, v126
	v_cndmask_b32_e64 v81, v81, v90, s[20:21]
	v_mul_f32_e32 v90, 0x37800000, v81
	v_cndmask_b32_e32 v81, v81, v90, vcc
	v_cmp_class_f32_e32 vcc, v88, v181
	s_lshl_b32 s40, s22, 2
	v_add_f32_e32 v45, v69, v89
	v_cndmask_b32_e32 v81, v81, v88, vcc
	v_max_f32_e32 v81, 0x2b8cbccc, v81
	v_div_scale_f32 v88, s[20:21], v81, v81, 1.0
	v_rcp_f32_e32 v90, v88
	s_mov_b64 s[20:21], s[92:93]
	s_cmp_eq_u32 s28, 0
	s_cselect_b64 s[24:25], -1, 0
	v_fma_f32 v44, -v88, v90, 1.0
	v_fmac_f32_e32 v90, v44, v90
	v_div_scale_f32 v44, vcc, 1.0, v81, 1.0
	v_mul_f32_e32 v46, v44, v90
	v_fma_f32 v47, -v88, v46, v44
	v_fmac_f32_e32 v46, v47, v90
	v_fma_f32 v44, -v88, v46, v44
	v_div_fmas_f32 v44, v44, v90, v46
	v_div_fixup_f32 v44, v44, v81, 1.0
	v_ashrrev_i32_e32 v81, 31, v80
	v_lshlrev_b64 v[46:47], 6, v[80:81]
	s_waitcnt lgkmcnt(0)
	v_lshl_add_u64 v[46:47], s[20:21], 0, v[46:47]
	v_lshl_add_u64 v[46:47], v[46:47], 0, s[40:41]
	global_store_dword v[46:47], v45, off
	v_lshl_add_u32 v46, v146, 2, 0
	v_add_u32_e32 v69, 0x1b400, v46
	ds_read_b128 v[46:49], v69
	ds_read_b128 v[78:81], v69 offset:256
	s_lshl_b64 s[22:23], s[26:27], 8
	s_cmp_gt_u32 s28, 1
	ds_read_b128 v[88:91], v69 offset:512
	s_waitcnt lgkmcnt(2)
	v_pk_add_f32 v[48:49], v[48:49], 0 op_sel_hi:[1,0]
	s_cselect_b64 vcc, -1, 0
	v_cndmask_b32_e64 v93, v49, 0, s[24:25]
	v_cndmask_b32_e64 v92, v48, 0, s[24:25]
	s_waitcnt lgkmcnt(1)
	v_pk_add_f32 v[94:95], v[80:81], v[92:93]
	v_pk_add_f32 v[46:47], v[46:47], 0 op_sel_hi:[1,0]
	v_cndmask_b32_e32 v97, v93, v95, vcc
	v_cndmask_b32_e32 v96, v92, v94, vcc
	ds_read_b128 v[92:95], v69 offset:768
	v_cndmask_b32_e64 v101, v47, 0, s[24:25]
	v_cndmask_b32_e64 v100, v46, 0, s[24:25]
	v_pk_add_f32 v[46:47], v[46:47], v[78:79]
	v_pk_add_f32 v[78:79], v[78:79], v[100:101]
	s_cmp_eq_u32 s28, 3
	v_cndmask_b32_e32 v79, v101, v79, vcc
	v_cndmask_b32_e32 v78, v100, v78, vcc
	s_waitcnt lgkmcnt(1)
	v_pk_add_f32 v[98:99], v[90:91], v[96:97]
	s_cselect_b64 s[20:21], -1, 0
	v_pk_add_f32 v[48:49], v[48:49], v[80:81]
	v_pk_add_f32 v[80:81], v[46:47], v[88:89]
	v_pk_add_f32 v[46:47], v[88:89], v[78:79]
	v_pk_add_f32 v[48:49], v[48:49], v[90:91]
	v_cndmask_b32_e64 v89, v97, v99, s[20:21]
	v_cndmask_b32_e64 v88, v96, v98, s[20:21]
	v_cndmask_b32_e64 v79, v79, v47, s[20:21]
	v_cndmask_b32_e64 v78, v78, v46, s[20:21]
	s_waitcnt lgkmcnt(0)
	v_pk_add_f32 v[46:47], v[48:49], v[94:95]
	v_pk_add_f32 v[48:49], v[80:81], v[92:93]
	v_pk_add_f32 v[42:43], v[42:43], v[88:89]
	v_pk_add_f32 v[40:41], v[40:41], v[78:79]
	v_sub_f32_e32 v91, v46, v42
	v_sub_f32_e32 v79, v48, v40
	v_sub_f32_e32 v69, v47, v43
	v_sub_f32_e32 v89, v49, v41
	v_exp_f32_e32 v78, v40
	v_exp_f32_e64 v80, -v40
	v_sub_f32_e32 v40, v40, v154
	v_exp_f32_e32 v88, v79
	v_exp_f32_e32 v79, v41
	v_exp_f32_e64 v81, -v41
	v_sub_f32_e32 v41, v41, v155
	v_exp_f32_e32 v90, v42
	v_exp_f32_e64 v92, -v42
	v_sub_f32_e32 v42, v42, v152
	v_exp_f32_e32 v94, v91
	v_exp_f32_e32 v91, v43
	v_exp_f32_e64 v93, -v43
	v_sub_f32_e32 v43, v43, v153
	v_mul_u32_u24_e32 v45, 0x48, v126
	v_exp_f32_e32 v40, v40
	v_exp_f32_e32 v41, v41
	v_exp_f32_e32 v42, v42
	v_exp_f32_e32 v43, v43
	v_lshlrev_b32_e32 v45, 1, v45
	v_pk_mul_f32 v[84:85], v[84:85], v[44:45] op_sel_hi:[1,0]
	v_pk_mul_f32 v[86:87], v[86:87], v[44:45] op_sel_hi:[1,0]
	v_exp_f32_e32 v89, v89
	v_pk_mul_f32 v[72:73], v[72:73], v[86:87]
	v_pk_mul_f32 v[74:75], v[74:75], v[84:85]
	v_pk_mul_f32 v[66:67], v[66:67], v[90:91]
	v_pk_mul_f32 v[64:65], v[64:65], v[78:79]
	v_pk_mul_f32 v[78:79], v[76:77], v[92:93]
	v_pk_mul_f32 v[90:91], v[70:71], v[80:81]
	v_exp_f32_e32 v95, v69
	v_pk_mul_f32 v[92:93], v[74:75], v[92:93]
	v_pk_mul_f32 v[80:81], v[72:73], v[80:81]
	v_pk_mul_f32 v[42:43], v[84:85], v[42:43]
	v_pk_mul_f32 v[84:85], v[86:87], v[40:41]
	v_add3_u32 v40, 0, v45, v147
	v_cvt_pk_bf16_f32 v64, v64, v65
	v_cvt_pk_bf16_f32 v65, v66, v67
	v_cvt_pk_bf16_f32 v66, v90, v91
	v_cvt_pk_bf16_f32 v67, v78, v79
	ds_write2st64_b64 v40, v[64:65], v[66:67] offset0:72 offset1:90
	v_cvt_pk_bf16_f32 v64, v80, v81
	v_cvt_pk_bf16_f32 v65, v92, v93
	v_cvt_pk_bf16_f32 v66, v84, v85
	v_cvt_pk_bf16_f32 v67, v42, v43
	v_lshlrev_b32_e32 v102, 1, v126
	ds_write2st64_b64 v40, v[64:65], v[66:67] offset0:108 offset1:126
	v_mul_lo_u32 v64, v146, s50
	v_pk_mul_f32 v[70:71], v[70:71], v[88:89]
	v_pk_mul_f32 v[72:73], v[72:73], v[88:89]
	v_cvt_pk_bf16_f32 v41, v82, v83
	v_add3_u32 v42, s55, v102, v64
	v_add3_u32 v43, s56, v102, v64
	s_cmp_lg_u32 s28, 0
	v_pk_mul_f32 v[76:77], v[76:77], v[94:95]
	v_pk_mul_f32 v[74:75], v[74:75], v[94:95]
	v_cvt_pk_bf16_f32 v45, v54, v55
	v_cvt_pk_bf16_f32 v55, v70, v71
	v_cvt_pk_bf16_f32 v70, v72, v73
	ds_write_b16 v42, v66
	ds_write_b16_d16_hi v42, v66 offset:144
	ds_write_b16 v42, v67 offset:288
	ds_write_b16_d16_hi v42, v67 offset:432
	ds_write_b16 v43, v41
	ds_write_b16_d16_hi v43, v41 offset:144
	ds_write_b16 v43, v45 offset:288
	ds_write_b16_d16_hi v43, v45 offset:432
	v_add3_u32 v54, s57, v102, v64
	v_add3_u32 v41, s58, v102, v64
	v_cvt_pk_bf16_f32 v69, v76, v77
	v_cvt_pk_bf16_f32 v71, v74, v75
	ds_write_b16 v54, v55
	ds_write_b16_d16_hi v54, v55 offset:144
	ds_write_b16 v54, v69 offset:288
	ds_write_b16_d16_hi v54, v69 offset:432
	ds_write_b16 v41, v70
	ds_write_b16_d16_hi v41, v70 offset:144
	ds_write_b16 v41, v71 offset:288
	ds_write_b16_d16_hi v41, v71 offset:432
	s_cbranch_scc1 .LBB0_197
	s_mov_b64 s[30:31], s[94:95]
	v_exp_f32_e32 v64, v48
	v_exp_f32_e32 v65, v49
	v_exp_f32_e32 v66, v46
	v_exp_f32_e32 v67, v47
	s_waitcnt lgkmcnt(0)
	s_add_u32 s30, s30, s22
	v_ashrrev_i32_e32 v147, 31, v146
	s_addc_u32 s31, s31, s23
	v_lshl_add_u64 v[46:47], v[146:147], 2, s[30:31]
	global_store_dwordx4 v[46:47], v[64:67], off
; __device__ __forceinline__ void st_bf4(bf16_t* p, f32x4 v) { u32x2 u; u.x = pk_bf16(v[0], v[1]); u.y = pk_bf16(v[2], v[3]); *(u32x2*)p = u; }
; __device__ __forceinline__ void phase_prep(const Params& p, unsigned char* shm) {
;     ...
; #pragma unroll
;             for (int n = 0; n < 2; ++n) {
;                 const int c4 = 32 * chh + 16 * n + 4 * fq;
;                 f32x4 pre = (f32x4){0.f, 0.f, 0.f, 0.f}, total = (f32x4){0.f, 0.f, 0.f, 0.f};
; #pragma unroll
;                 for (int t2 = 0; t2 < 4; ++t2) { const f32x4 x = *(const f32x4*)(tot + t2 * 64 + c4); total += x; if (t2 < tt) pre += x; }
;                 const f32x4 csum = pre + cs[n];
;                 f32x4 eg, eng, egm, etc; const f32x4 ncs = -csum, cml = csum - lw[n], tmc = total - csum;
; #pragma unroll
;                 for (int j = 0; j < 4; ++j) { eg[j] = __builtin_amdgcn_exp2f(csum[j]); eng[j] = __builtin_amdgcn_exp2f(ncs[j]); egm[j] = __builtin_amdgcn_exp2f(cml[j]); etc[j] = __builtin_amdgcn_exp2f(tmc[j]); }
;                 const f32x4 kkn = kkv[n] * inv, bb = kkn * av[n];
;                 const f32x4 qt = rm[n] * eg, kt = kp[n] * eng, bt = bb * eng, kkt = kkn * egm, kpp = kp[n] * etc, bpp = bb * etc;
;                 st_bf4(Qt + tk * LD + c4, qt); st_bf4(Kt + tk * LD + c4, kt); st_bf4(Bt + tk * LD + c4, bt);
;                 const u32x2 kkw = pk_bf4(kkt), vmw = pk_bf4(vm[n]), kpw = pk_bf4(kpp), bpw = pk_bf4(bpp);
;                 *(u32x2*)(KKt + tk * LD + c4) = kkw;
;                 { bf16_t* d = KKtT + c4 * LD + tk; d[0] = (bf16_t)kkw.x; d[LD] = (bf16_t)(kkw.x >> 16); d[2 * LD] = (bf16_t)kkw.y; d[3 * LD] = (bf16_t)(kkw.y >> 16); }
;                 { bf16_t* d = VmT + c4 * LD + tk; d[0] = (bf16_t)vmw.x; d[LD] = (bf16_t)(vmw.x >> 16); d[2 * LD] = (bf16_t)vmw.y; d[3 * LD] = (bf16_t)(vmw.y >> 16); }
;                 { bf16_t* d = KpT + c4 * LD + tk; d[0] = (bf16_t)kpw.x; d[LD] = (bf16_t)(kpw.x >> 16); d[2 * LD] = (bf16_t)kpw.y; d[3 * LD] = (bf16_t)(kpw.y >> 16); }
;                 { bf16_t* d = BpT + c4 * LD + tk; d[0] = (bf16_t)bpw.x; d[LD] = (bf16_t)(bpw.x >> 16); d[2 * LD] = (bf16_t)bpw.y; d[3 * LD] = (bf16_t)(bpw.y >> 16); }
;                 if (tt == 0) { f32x4 g; g[0] = __builtin_amdgcn_exp2f(total[0]); g[1] = __builtin_amdgcn_exp2f(total[1]); g[2] = __builtin_amdgcn_exp2f(total[2]); g[3] = __builtin_amdgcn_exp2f(total[3]); *(f32x4*)(p.GCG + (size_t)item * 64 + c4) = g; }
.LBB0_197:
	s_nop 1
	v_lshlrev_b32_e32 v64, 16, v38
	v_and_b32_e32 v65, 0xffff0000, v38
	v_lshlrev_b32_e32 v38, 16, v39
	v_and_b32_e32 v39, 0xffff0000, v39
	v_lshlrev_b32_e32 v46, 16, v32
	v_and_b32_e32 v32, 0xffff0000, v32
	v_and_b32_e32 v47, 0xffff0000, v33
	v_add_u32_e32 v69, 0x1b400, v190
	v_lshlrev_b32_e32 v55, 16, v33
	v_sub_f32_e32 v33, v32, v65
	v_sub_f32_e32 v32, v46, v64
	v_sub_f32_e32 v67, v47, v39
	ds_read_b128 v[46:49], v69
	v_sub_f32_e32 v66, v55, v38
	v_pk_fma_f32 v[38:39], v[30:31], v[66:67], v[38:39]
	v_pk_fma_f32 v[32:33], v[28:29], v[32:33], v[64:65]
	ds_read_b128 v[28:31], v69 offset:256
	s_waitcnt lgkmcnt(1)
	v_pk_add_f32 v[48:49], v[48:49], 0 op_sel_hi:[1,0]
	v_pk_add_f32 v[46:47], v[46:47], 0 op_sel_hi:[1,0]
	v_cndmask_b32_e64 v65, v49, 0, s[24:25]
	v_cndmask_b32_e64 v64, v48, 0, s[24:25]
	v_cndmask_b32_e64 v67, v47, 0, s[24:25]
	v_cndmask_b32_e64 v66, v46, 0, s[24:25]
	s_waitcnt lgkmcnt(0)
	v_pk_add_f32 v[70:71], v[48:49], v[30:31]
	v_pk_add_f32 v[72:73], v[46:47], v[28:29]
	v_pk_add_f32 v[46:47], v[30:31], v[64:65]
	v_pk_add_f32 v[48:49], v[28:29], v[66:67]
	ds_read_b128 v[28:31], v69 offset:512
	v_cndmask_b32_e32 v65, v65, v47, vcc
	v_cndmask_b32_e32 v64, v64, v46, vcc
	v_cndmask_b32_e32 v67, v67, v49, vcc
	v_cndmask_b32_e32 v66, v66, v48, vcc
	ds_read_b128 v[46:49], v69 offset:768
	s_waitcnt lgkmcnt(1)
	v_pk_add_f32 v[70:71], v[70:71], v[30:31]
	v_pk_add_f32 v[72:73], v[72:73], v[28:29]
	v_pk_add_f32 v[30:31], v[30:31], v[64:65]
	v_pk_add_f32 v[28:29], v[28:29], v[66:67]
	v_cndmask_b32_e64 v65, v65, v31, s[20:21]
	v_cndmask_b32_e64 v64, v64, v30, s[20:21]
	v_cndmask_b32_e64 v67, v67, v29, s[20:21]
	v_cndmask_b32_e64 v66, v66, v28, s[20:21]
	s_waitcnt lgkmcnt(0)
	v_pk_add_f32 v[28:29], v[70:71], v[48:49]
	v_pk_add_f32 v[30:31], v[72:73], v[46:47]
	v_pk_add_f32 v[26:27], v[26:27], v[64:65]
	v_pk_add_f32 v[24:25], v[24:25], v[66:67]
	v_sub_f32_e32 v67, v28, v26
	v_sub_f32_e32 v47, v30, v24
	v_sub_f32_e32 v55, v29, v27
	v_sub_f32_e32 v65, v31, v25
	v_exp_f32_e32 v46, v24
	v_exp_f32_e64 v48, -v24
	v_sub_f32_e32 v24, v24, v150
	v_exp_f32_e32 v64, v47
	v_exp_f32_e32 v47, v25
	v_exp_f32_e64 v49, -v25
	v_sub_f32_e32 v25, v25, v151
	v_exp_f32_e32 v66, v26
	v_exp_f32_e64 v70, -v26
	v_sub_f32_e32 v26, v26, v148
	v_exp_f32_e32 v72, v67
	v_exp_f32_e32 v67, v27
	v_exp_f32_e64 v71, -v27
	v_sub_f32_e32 v27, v27, v149
	v_exp_f32_e32 v24, v24
	v_exp_f32_e32 v25, v25
	v_exp_f32_e32 v65, v65
	v_exp_f32_e32 v26, v26
	v_exp_f32_e32 v27, v27
	v_exp_f32_e32 v73, v55
	v_mov_b32_e32 v45, v44
	v_mov_b32_e32 v74, v44
	v_mov_b32_e32 v75, v44
	v_pk_mul_f32 v[58:59], v[58:59], v[74:75]
	v_pk_mul_f32 v[44:45], v[60:61], v[44:45]
	v_pk_mul_f32 v[52:53], v[52:53], v[58:59]
	v_pk_mul_f32 v[50:51], v[50:51], v[44:45]
	v_pk_mul_f32 v[34:35], v[34:35], v[66:67]
	v_pk_mul_f32 v[46:47], v[62:63], v[46:47]
	v_pk_mul_f32 v[60:61], v[56:57], v[70:71]
	v_pk_mul_f32 v[62:63], v[36:37], v[48:49]
	v_pk_mul_f32 v[66:67], v[52:53], v[70:71]
	v_pk_mul_f32 v[48:49], v[50:51], v[48:49]
	v_pk_mul_f32 v[26:27], v[58:59], v[26:27]
	v_pk_mul_f32 v[24:25], v[44:45], v[24:25]
	v_pk_mul_f32 v[36:37], v[36:37], v[64:65]
	v_pk_mul_f32 v[52:53], v[52:53], v[72:73]
	v_cvt_pk_bf16_f32 v46, v46, v47
	v_cvt_pk_bf16_f32 v47, v34, v35
	v_cvt_pk_bf16_f32 v34, v62, v63
	v_cvt_pk_bf16_f32 v35, v60, v61
	v_add_u32_e32 v40, 32, v40
	v_pk_mul_f32 v[44:45], v[56:57], v[72:73]
	v_pk_mul_f32 v[50:51], v[50:51], v[64:65]
	ds_write2st64_b64 v40, v[46:47], v[34:35] offset0:72 offset1:90
	v_cvt_pk_bf16_f32 v34, v48, v49
	v_cvt_pk_bf16_f32 v35, v66, v67
	v_cvt_pk_bf16_f32 v24, v24, v25
	v_cvt_pk_bf16_f32 v25, v26, v27
	v_cvt_pk_bf16_f32 v26, v32, v33
	v_cvt_pk_bf16_f32 v32, v36, v37
	v_cvt_pk_bf16_f32 v37, v52, v53
	s_andn2_b64 vcc, exec, s[24:25]
	v_cvt_pk_bf16_f32 v27, v38, v39
	v_cvt_pk_bf16_f32 v33, v44, v45
	v_cvt_pk_bf16_f32 v36, v50, v51
	ds_write2st64_b64 v40, v[34:35], v[24:25] offset0:108 offset1:126
	ds_write_b16 v42, v24 offset:2304
	ds_write_b16_d16_hi v42, v24 offset:2448
	ds_write_b16 v42, v25 offset:2592
	ds_write_b16_d16_hi v42, v25 offset:2736
	ds_write_b16 v43, v26 offset:2304
	ds_write_b16_d16_hi v43, v26 offset:2448
	ds_write_b16 v43, v27 offset:2592
	ds_write_b16_d16_hi v43, v27 offset:2736
	ds_write_b16 v54, v32 offset:2304
	ds_write_b16_d16_hi v54, v32 offset:2448
	ds_write_b16 v54, v33 offset:2592
	ds_write_b16_d16_hi v54, v33 offset:2736
	ds_write_b16 v41, v36 offset:2304
	ds_write_b16_d16_hi v41, v36 offset:2448
	ds_write_b16 v41, v37 offset:2592
	ds_write_b16_d16_hi v41, v37 offset:2736
	s_cbranch_vccnz .LBB0_199
	s_mov_b64 s[20:21], s[94:95]
	v_exp_f32_e32 v24, v30
	v_exp_f32_e32 v25, v31
	v_exp_f32_e32 v26, v28
	v_exp_f32_e32 v27, v29
	s_waitcnt lgkmcnt(0)
	s_add_u32 s20, s20, s22
	s_addc_u32 s21, s21, s23
	v_ashrrev_i32_e32 v147, 31, v146
	v_lshl_add_u64 v[28:29], v[146:147], 2, s[20:21]
	global_store_dwordx4 v[28:29], v[24:27], off offset:64

; __device__ __forceinline__ void st_bf4(bf16_t* p, f32x4 v) { u32x2 u; u.x = pk_bf16(v[0], v[1]); u.y = pk_bf16(v[2], v[3]); *(u32x2*)p = u; }
; #define MFMA16(a, b, c) __builtin_amdgcn_mfma_f32_16x16x32_bf16(a, b, c, 0, 0, 0)
; __device__ __forceinline__ void phase_prep(const Params& p, unsigned char* shm) {
;     ...
;             for (int idx = wid; idx < 64; idx += 7) {
;                 const int mat = idx >> 4, nt = (idx >> 2) & 3, ms = idx & 3;
;                 f32x4 c = (f32x4){0.f, 0.f, 0.f, 0.f};
;                 if (mat == 3) {
;                     c = MFMA16(ldfrag(KpT, LD, 16 * nt, 0, fr, fq), ldfrag(VmT, LD, 16 * ms, 0, fr, fq), c);
;                     c = MFMA16(ldfrag(KpT, LD, 16 * nt, 32, fr, fq), ldfrag(VmT, LD, 16 * ms, 32, fr, fq), c);
;                     st_bf4(VKt + (16 * ms + fr) * LD + 16 * nt + 4 * fq, c);
;                 } else {
;                     const bf16_t* asrc = mat == 2 ? Bt : Kt; const bf16_t* bsrc = mat == 0 ? KKt : Qt;
;                     if (ms <= nt) {
;                         c = MFMA16(ldfrag(asrc, LD, 16 * ms, 0, fr, fq), ldfrag(bsrc, LD, 16 * nt, 0, fr, fq), c);
;                         c = MFMA16(ldfrag(asrc, LD, 16 * ms, 32, fr, fq), ldfrag(bsrc, LD, 16 * nt, 32, fr, fq), c);
;                         if (ms == nt) {
; #pragma unroll
;                             for (int j = 0; j < 4; ++j) { const int sx = 4 * fq + j; const bool keep = mat ? (sx <= fr) : (sx < fr); if (!keep) c[j] = 0.f; }
;                         }
;                     }
;                     const int tix = 16 * nt + fr, six = 16 * ms + 4 * fq;
;                     if (mat == 0) st_bf4(Aak + tix * LD + six, c); else if (mat == 1) st_bf4(Aqk + tix * LD + six, c); else st_bf4(p.AQBG + chbase + tix * 64 + six, c);
;                 }
.LBB0_218:
	s_cmp_lg_u32 s75, 1
	s_cbranch_scc0 .LBB0_220
	s_mov_b64 s[34:35], s[96:97]
	s_lshl_b64 s[46:47], s[44:45], 1
	v_lshlrev_b32_e32 v126, 7, v32
	v_mov_b32_e32 v31, v127
	v_cvt_pk_bf16_f32 v34, v24, v25
	s_waitcnt lgkmcnt(0)
	s_add_u32 s34, s34, s46
	s_addc_u32 s35, s35, s47
	v_lshl_add_u64 v[36:37], s[34:35], 0, v[126:127]
	v_lshl_add_u64 v[36:37], v[30:31], 1, v[36:37]
	v_cvt_pk_bf16_f32 v35, v26, v27
	global_store_dwordx2 v[36:37], v[34:35], off
	s_mov_b64 s[34:35], 0

; __device__ __forceinline__ void st_bf4(bf16_t* p, f32x4 v) { u32x2 u; u.x = pk_bf16(v[0], v[1]); u.y = pk_bf16(v[2], v[3]); *(u32x2*)p = u; }
; #define MFMA16(a, b, c) __builtin_amdgcn_mfma_f32_16x16x32_bf16(a, b, c, 0, 0, 0)
; __device__ __forceinline__ void phase_prep(const Params& p, unsigned char* shm) {
;     ...
;         {
;             *(u32x4*)(p.VKG + chbase + crow * 64 + cseg) = *(const u32x4*)(VKt + crow * LD + cseg);
;             *(u32x4*)(p.YVG + chbase + crow * 64 + cseg) = *(const u32x4*)(YVt + crow * LD + cseg);
; #pragma unroll
;             for (int i = 0; i < 4; ++i) {
;                 const int idx = wid + 8 * i; f32x4 c = (f32x4){0.f, 0.f, 0.f, 0.f};
;                 if (idx < 16) { const int mk = idx >> 2, nt = idx & 3;
;                     c = MFMA16(ldfrag(KKtT, LD, 16 * mk, 0, fr, fq), ldfrag(Tm, LD, 16 * nt, 0, fr, fq), c);
;                     c = MFMA16(ldfrag(KKtT, LD, 16 * mk, 32, fr, fq), ldfrag(Tm, LD, 16 * nt, 32, fr, fq), c);
;                     st_bf4(W1t + (16 * nt + fr) * LD + 16 * mk + 4 * fq, -c);
;                 } else { const int i2 = idx - 16, mt = i2 >> 2, nv = i2 & 3;
;                     c = MFMA16(ldfrag(Tm, LD, 16 * mt, 0, fr, fq), ldfrag(XT, LD, 16 * nv, 0, fr, fq), c);
;                     c = MFMA16(ldfrag(Tm, LD, 16 * mt, 32, fr, fq), ldfrag(XT, LD, 16 * nv, 32, fr, fq), c);
;                     st_bf4(U0t + (16 * nv + fr) * LD + 16 * mt + 4 * fq, -c);
;                 }
;             }
.LBB0_256:
	s_mov_b64 s[20:21], s[98:99]
	s_mov_b64 s[22:23], s[100:101]
	v_mul_lo_u32 v24, v186, s54
	v_lshlrev_b32_e32 v26, 1, v24
	v_add3_u32 v24, 0, v26, v144
	ds_read_b128 v[28:31], v24 offset:26624
	s_lshl_b64 s[18:19], s[44:45], 1
	v_lshlrev_b32_e32 v24, 6, v186
	s_waitcnt lgkmcnt(0)
	s_add_u32 s22, s22, s18
	v_ashrrev_i32_e32 v25, 31, v24
	s_addc_u32 s23, s23, s19
	v_lshlrev_b64 v[24:25], 1, v[24:25]
	v_lshl_add_u64 v[32:33], s[22:23], 0, v[24:25]
	v_mov_b32_e32 v145, v127
	v_add3_u32 v27, s57, v26, v144
	v_lshl_add_u64 v[36:37], v[32:33], 0, v[144:145]
	ds_read_b128 v[32:35], v27
	s_add_u32 s20, s20, s18
	s_addc_u32 s21, s21, s19
	global_store_dwordx4 v[36:37], v[28:31], off
	v_and_or_b32 v27, s72, 48, v185
	s_lshl_b32 s22, s71, 2
	v_lshl_add_u64 v[28:29], s[20:21], 0, v[24:25]
	v_lshl_add_u64 v[28:29], v[28:29], 0, v[144:145]
	s_waitcnt lgkmcnt(0)
	global_store_dwordx4 v[28:29], v[32:35], off
	v_mul_u32_u24_e32 v29, 0x90, v27
	v_add3_u32 v27, 0, v29, v40
	v_add3_u32 v28, s56, v29, v41
	s_cmp_gt_i32 s71, 15
	s_mov_b64 s[20:21], -1
	s_cbranch_scc0 .LBB0_264
	s_and_b32 s20, s22, 0x7ffffff0
	s_sub_i32 s20, s20, 64
	v_or_b32_e32 v30, s20, v185
	v_mul_lo_u32 v30, v30, s50
	v_add3_u32 v34, 0, v30, v40
	ds_read_b128 v[30:33], v34 offset:17408
	ds_read_b128 v[34:37], v34 offset:17472
	ds_read_b128 v[42:45], v27 offset:64512
	ds_read_b128 v[46:49], v27 offset:64576
	v_lshl_add_u32 v38, s20, 1, v28
	s_waitcnt lgkmcnt(1)
	v_mfma_f32_16x16x32_bf16 v[30:33], v[30:33], v[42:45], 0
	s_waitcnt lgkmcnt(0)
	v_mfma_f32_16x16x32_bf16 v[30:33], v[34:37], v[46:49], v[30:33]
	s_nop 7
	v_xor_b32_e32 v33, 0x80000000, v33
	v_xor_b32_e32 v32, 0x80000000, v32
	v_xor_b32_e32 v31, 0x80000000, v31
	v_xor_b32_e32 v30, 0x80000000, v30
	v_cvt_pk_bf16_f32 v30, v30, v31
	v_cvt_pk_bf16_f32 v31, v32, v33
	ds_write_b64 v38, v[30:31]
	v_add3_u32 v29, s58, v29, v41
	s_cbranch_execz .LBB0_265

; __device__ __forceinline__ void seq_item(const Params& p, unsigned char* shm, int row0, int nchunks, int h, const float* S0, float* Sout) {
;     constexpr int LD = 72, SLOT = 4 * 64 * LD + 128;
;     bf16_t* Sb = (bf16_t*)shm; bf16_t* UT = Sb + 64 * LD; bf16_t* ring = UT + 64 * LD;
;     const int tid = threadIdx.x, lane = tid & 63, wid = tid >> 6, fr = lane & 15, fq = lane >> 4;
;     const int m = wid >> 1, nv0 = 2 * (wid & 1), c0 = 16 * m + 4 * fq;
;     const int crow = tid >> 3, cseg = (tid & 7) * 8;
;     f32x4 S[2];
; #pragma unroll
;     for (int q = 0; q < 2; ++q) S[q] = S0 ? *(const f32x4*)(S0 + (16 * (nv0 + q) + fr) * 64 + c0) : (f32x4){0.f, 0.f, 0.f, 0.f};
;     const int chi0 = (row0 >> 6) * 16 + h, last = nchunks - 1;
;     struct Stage { u32x4 g[4]; f32x4 gc; };
;     auto gload = [&](int ci, Stage& G) {
;         const size_t cb = (size_t)(chi0 + ci * 16) * 4096 + crow * 64 + cseg;
;         G.g[0] = *(const u32x4*)(p.W1G + cb); G.g[1] = *(const u32x4*)(p.BPG + cb); G.g[2] = *(const u32x4*)(p.U0G + cb); G.g[3] = *(const u32x4*)(p.VKG + cb);
;         G.gc = *(const f32x4*)(p.GCG + (size_t)(chi0 + ci * 16) * 64 + (tid & 15) * 4);
;     };
;     auto park = [&](int slot, const Stage& G) {
;         bf16_t* d = ring + slot * SLOT;
; #pragma unroll
;         for (int a = 0; a < 4; ++a) *(u32x4*)(d + a * 64 * LD + crow * LD + cseg) = G.g[a];
;         if (tid < 16) *(f32x4*)((float*)(d + 4 * 64 * LD) + tid * 4) = G.gc;
;     };
;     auto body = [&](int ci, int slot, int pslot, const Stage& G) {
;         const bf16_t* W1s = ring + slot * SLOT; const bf16_t* BPs = W1s + 64 * LD; const bf16_t* U0s = BPs + 64 * LD; const bf16_t* VKs = U0s + 64 * LD;
;         const float* GCs = (const float*)(VKs + 64 * LD);
;         const size_t cb = (size_t)(chi0 + ci * 16) * 4096;
; #pragma unroll
;         for (int q = 0; q < 2; ++q) *(u32x2*)(Sb + (16 * (nv0 + q) + fr) * LD + c0) = pk_bf4(S[q]);
;         LDS_BARRIER();
;         park(pslot, G);
;         *(u32x4*)(p.Z + (size_t)(row0 + ci * 64 + crow) * LDZ + ZC_S + h * 64 + cseg) = *(const u32x4*)(Sb + crow * LD + cseg);
;         const bf16x8 w10 = ldfrag(W1s, LD, 16 * m, 0, fr, fq), w11 = ldfrag(W1s, LD, 16 * m, 32, fr, fq);
; #pragma unroll
;         for (int q = 0; q < 2; ++q) {
;             const int v = 16 * (nv0 + q) + fr;
;             f32x4 acc = up_bf4(*(const u32x2*)(U0s + v * LD + c0));
.LBB0_431:
	s_andn2_b64 vcc, exec, s[2:3]
	s_cbranch_vccnz .LBB0_443
	s_lshl_b32 s2, s40, 9
	s_and_b32 s23, s2, 0xffffe000
	s_and_b32 s20, s40, 15
	s_ashr_i32 s21, s23, 2
	s_or_b32 s6, s21, s20
	s_ashr_i32 s7, s6, 31
	s_load_dwordx8 s[12:19], s[0:1], 0x108
	s_load_dwordx2 s[90:91], s[0:1], 0xb8
	s_load_dwordx2 s[92:93], s[0:1], 0x100
	s_lshl_b64 s[2:3], s[6:7], 12
	s_waitcnt vmcnt(2)
	v_lshlrev_b32_e32 v20, 6, v164
	v_mov_b32_e32 v21, 0
	v_and_b32_e32 v22, 56, v131
	v_lshl_add_u64 v[0:1], s[2:3], 0, v[20:21]
	v_or_b32_e32 v0, v0, v22
	v_lshlrev_b64 v[0:1], 1, v[0:1]
	s_waitcnt lgkmcnt(0)
	v_lshl_add_u64 v[2:3], s[12:13], 0, v[0:1]
	s_or_b32 s2, s6, 16
	global_load_dwordx4 v[24:27], v[2:3], off
	v_lshl_add_u64 v[2:3], s[14:15], 0, v[0:1]
	s_ashr_i32 s3, s2, 31
	global_load_dwordx4 v[28:31], v[2:3], off
	v_lshl_add_u64 v[2:3], s[16:17], 0, v[0:1]
	v_lshl_add_u64 v[0:1], s[18:19], 0, v[0:1]
	s_load_dwordx2 s[10:11], s[0:1], 0x130
	s_lshl_b64 s[4:5], s[2:3], 12
	global_load_dwordx4 v[36:39], v[0:1], off
	v_lshl_add_u64 v[0:1], s[4:5], 0, v[20:21]
	v_or_b32_e32 v0, v0, v22
	v_lshlrev_b64 v[0:1], 1, v[0:1]
	global_load_dwordx4 v[32:35], v[2:3], off
	v_lshl_add_u64 v[2:3], s[12:13], 0, v[0:1]
	s_lshl_b64 s[2:3], s[2:3], 8
	global_load_dwordx4 v[4:7], v[2:3], off
	v_lshl_add_u64 v[2:3], s[14:15], 0, v[0:1]
	s_waitcnt lgkmcnt(0)
	s_add_u32 s2, s10, s2
	global_load_dwordx4 v[12:15], v[2:3], off
	v_lshl_add_u64 v[2:3], s[16:17], 0, v[0:1]
	s_addc_u32 s3, s11, s3
	global_load_dwordx4 v[8:11], v[2:3], off
	v_lshl_add_u64 v[40:41], s[18:19], 0, v[0:1]
	global_load_dwordx4 v[0:3], v120, s[2:3]
	global_load_dwordx4 v[16:19], v[40:41], off
	s_load_dwordx2 s[2:3], s[0:1], 0xb0
	v_mul_u32_u24_e32 v23, 0x48, v164
	v_lshlrev_b32_e32 v51, 1, v23
	v_lshlrev_b32_e32 v48, 1, v22
	v_cmp_gt_u32_e64 s[8:9], 16, v133
	v_add3_u32 v60, 0, v51, v48
	v_lshl_add_u32 v23, v134, 2, 0
	s_waitcnt vmcnt(8)
	ds_write_b128 v60, v[24:27] offset:18432
	s_waitcnt vmcnt(7)
	ds_write_b128 v60, v[28:31] offset:27648
	s_waitcnt vmcnt(5)
	ds_write_b128 v60, v[32:35] offset:36864
	ds_write_b128 v60, v[36:39] offset:46080
	s_and_saveexec_b64 s[4:5], s[8:9]
	s_cbranch_execz .LBB0_434
	s_lshl_b64 s[24:25], s[6:7], 8
	s_add_u32 s24, s10, s24
	s_addc_u32 s25, s11, s25
	global_load_dwordx4 v[24:27], v120, s[24:25]
	s_waitcnt vmcnt(0)
	ds_write_b128 v23, v[24:27] offset:55296

; __device__ __forceinline__ void seq_item(const Params& p, unsigned char* shm, int row0, int nchunks, int h, const float* S0, float* Sout) {
;     ...
;     auto body = [&](int ci, int slot, int pslot, const Stage& G) {
;         const bf16_t* W1s = ring + slot * SLOT; const bf16_t* BPs = W1s + 64 * LD; const bf16_t* U0s = BPs + 64 * LD; const bf16_t* VKs = U0s + 64 * LD;
;         const float* GCs = (const float*)(VKs + 64 * LD);
;         const size_t cb = (size_t)(chi0 + ci * 16) * 4096;
; #pragma unroll
;         for (int q = 0; q < 2; ++q) *(u32x2*)(Sb + (16 * (nv0 + q) + fr) * LD + c0) = pk_bf4(S[q]);
;         LDS_BARRIER();
;         park(pslot, G);
;         *(u32x4*)(p.Z + (size_t)(row0 + ci * 64 + crow) * LDZ + ZC_S + h * 64 + cseg) = *(const u32x4*)(Sb + crow * LD + cseg);
;         const bf16x8 w10 = ldfrag(W1s, LD, 16 * m, 0, fr, fq), w11 = ldfrag(W1s, LD, 16 * m, 32, fr, fq);
; #pragma unroll
;         for (int q = 0; q < 2; ++q) {
;             const int v = 16 * (nv0 + q) + fr;
;             f32x4 acc = up_bf4(*(const u32x2*)(U0s + v * LD + c0));
;             acc = MFMA16(w10, ldfrag(Sb, LD, 16 * (nv0 + q), 0, fr, fq), acc);
;             acc = MFMA16(w11, ldfrag(Sb, LD, 16 * (nv0 + q), 32, fr, fq), acc);
;             *(u32x2*)(UT + v * LD + c0) = pk_bf4(acc);
;         }
;         LDS_BARRIER();
;         *(u32x4*)(p.UTG + cb + crow * 64 + cseg) = *(const u32x4*)(UT + crow * LD + cseg);
;         const bf16x8 bp0 = ldfrag(BPs, LD, 16 * m, 0, fr, fq), bp1 = ldfrag(BPs, LD, 16 * m, 32, fr, fq);
;         const f32x4 gc = *(const f32x4*)(GCs + c0);
; #pragma unroll
;         for (int q = 0; q < 2; ++q) {
;             const int v = 16 * (nv0 + q) + fr;
;             f32x4 acc = S[q] * gc + up_bf4(*(const u32x2*)(VKs + v * LD + c0));
;             acc = MFMA16(bp0, ldfrag(UT, LD, 16 * (nv0 + q), 0, fr, fq), acc);
;             acc = MFMA16(bp1, ldfrag(UT, LD, 16 * (nv0 + q), 32, fr, fq), acc);
;             S[q] = acc;
;         }
;     };
;     Stage A, B;
;     gload(0, A); gload(min(1, last), B);
;     park(0, A); park(1, B);
;     gload(min(2, last), A);
;     int scur = 0, spark = 2;
;     for (int ci = 0; ci < nchunks; ci += 2) {
;         gload(min(ci + 3, last), B);
;         body(ci, scur, spark, A);
;         scur = scur == 2 ? 0 : scur + 1; spark = spark == 2 ? 0 : spark + 1;
;         if (ci + 1 >= nchunks) break;
.LBB0_440:
	s_or_b64 exec, exec, s[10:11]
	s_mul_i32 s10, s28, 0x9100
	s_add_i32 s34, s10, 0
	v_lshlrev_b32_e32 v70, 1, v62
	v_lshlrev_b32_e32 v71, 1, v50
	v_add3_u32 v90, s34, v70, v71
	ds_read_b64 v[10:11], v90 offset:36864
	v_add3_u32 v80, s34, v65, v69
	s_mov_b64 s[20:21], s[90:91]
	ds_read_b128 v[0:3], v80 offset:18432
	ds_read_b128 v[4:7], v80 offset:18496
	ds_read_b128 v[12:15], v60
	s_waitcnt vmcnt(5)
	ds_read_b128 v[16:19], v66
	s_waitcnt lgkmcnt(0)
	v_lshlrev_b32_e32 v8, 16, v10
	v_and_b32_e32 v9, 0xffff0000, v10
	v_lshlrev_b32_e32 v10, 16, v11
	v_and_b32_e32 v11, 0xffff0000, v11
	ds_read_b128 v[72:75], v66 offset:64
	v_mov_b64_e32 v[76:77], s[20:21]
	v_mfma_f32_16x16x32_bf16 v[8:11], v[0:3], v[16:19], v[8:11]
	ds_read_b128 v[16:19], v67
	v_mad_i64_i32 v[76:77], s[10:11], v68, s27, v[76:77]
	s_waitcnt lgkmcnt(1)
	v_mfma_f32_16x16x32_bf16 v[8:11], v[4:7], v[72:75], v[8:11]
	s_add_i32 s23, s22, 1
	s_cmp_lg_u32 s22, 2
	s_cselect_b32 s29, s23, 0
	s_min_u32 s22, s26, 0x7b
	s_lshl_b32 s22, s22, 4
	s_nop 2
	v_cvt_pk_bf16_f32 v8, v8, v9
	v_cvt_pk_bf16_f32 v9, v10, v11
	ds_write_b64 v63, v[8:9] offset:9216
	ds_read_b64 v[10:11], v90 offset:39168
	v_lshl_add_u64 v[8:9], v[76:77], 0, s[4:5]
	v_lshl_add_u64 v[72:73], v[8:9], 0, v[48:49]
	v_add_co_u32_e32 v72, vcc, 0x1000, v72
	s_waitcnt lgkmcnt(0)
	v_lshlrev_b32_e32 v8, 16, v10
	v_and_b32_e32 v9, 0xffff0000, v10
	v_lshlrev_b32_e32 v10, 16, v11
	v_and_b32_e32 v11, 0xffff0000, v11
	v_addc_co_u32_e32 v73, vcc, 0, v73, vcc
	s_nop 0
	v_mfma_f32_16x16x32_bf16 v[0:3], v[0:3], v[16:19], v[8:11]
	global_store_dwordx4 v[72:73], v[12:15], off offset:2048
	s_add_i32 s22, s25, s22
	s_ashr_i32 s23, s22, 31
	ds_read_b128 v[8:11], v67 offset:64
	s_waitcnt lgkmcnt(0)
	v_mfma_f32_16x16x32_bf16 v[0:3], v[4:7], v[8:11], v[0:3]
	s_lshl_b64 s[30:31], s[22:23], 12
	s_lshl_b64 s[22:23], s[22:23], 8
	v_lshl_add_u64 v[16:17], v[54:55], 0, s[22:23]
	s_nop 4
	v_cvt_pk_bf16_f32 v0, v0, v1
	v_cvt_pk_bf16_f32 v1, v2, v3
	ds_write_b64 v64, v[0:1] offset:9216
	s_waitcnt lgkmcnt(0)
	s_barrier
	s_mov_b64 s[10:11], s[92:93]
	ds_read_b128 v[0:3], v60 offset:9216
	ds_read_b128 v[72:75], v66 offset:9216
	v_lshl_add_u32 v84, v50, 2, s34
	s_mul_i32 s22, s29, 0x9100
	s_waitcnt lgkmcnt(0)
	v_lshl_add_u64 v[4:5], s[10:11], 0, v[56:57]
	global_store_dwordx4 v[4:5], v[0:3], off
	global_load_dwordx4 v[16:19], v[16:17], off
	s_nop 0
	v_lshl_add_u64 v[0:1], s[30:31], 0, v[52:53]
	v_lshlrev_b64 v[12:13], 1, v[0:1]
	v_lshl_add_u64 v[0:1], s[12:13], 0, v[12:13]
	v_lshl_add_u64 v[4:5], s[14:15], 0, v[12:13]
	v_lshl_add_u64 v[8:9], s[16:17], 0, v[12:13]
	v_lshl_add_u64 v[12:13], s[18:19], 0, v[12:13]
	global_load_dwordx4 v[0:3], v[0:1], off
	s_add_i32 s30, s22, 0
	global_load_dwordx4 v[4:7], v[4:5], off
	s_nop 0
	global_load_dwordx4 v[8:11], v[8:9], off
	s_nop 0
	global_load_dwordx4 v[12:15], v[12:13], off
	ds_read_b64 v[88:89], v90 offset:46080
	ds_read_b128 v[76:79], v80 offset:27648
	ds_read_b128 v[80:83], v80 offset:27712
	ds_read_b128 v[84:87], v84 offset:55296
	ds_read_b64 v[92:93], v90 offset:48384
	s_waitcnt lgkmcnt(4)
	v_lshlrev_b32_e32 v90, 16, v88
	v_and_b32_e32 v91, 0xffff0000, v88
	v_lshlrev_b32_e32 v88, 16, v89
	v_and_b32_e32 v89, 0xffff0000, v89
	s_waitcnt lgkmcnt(1)
	v_pk_fma_f32 v[26:27], v[26:27], v[86:87], v[88:89]
	v_pk_fma_f32 v[24:25], v[24:25], v[84:85], v[90:91]
	s_nop 1
	v_mfma_f32_16x16x32_bf16 v[24:27], v[76:79], v[72:75], v[24:27]
	ds_read_b128 v[72:75], v66 offset:9280
	ds_read_b128 v[88:91], v67 offset:9216
	s_waitcnt lgkmcnt(1)
	v_mfma_f32_16x16x32_bf16 v[24:27], v[80:83], v[72:75], v[24:27]
	v_lshlrev_b32_e32 v72, 16, v92
	v_and_b32_e32 v73, 0xffff0000, v92
	v_lshlrev_b32_e32 v74, 16, v93
	v_and_b32_e32 v75, 0xffff0000, v93
	v_pk_fma_f32 v[22:23], v[22:23], v[86:87], v[74:75]
	v_pk_fma_f32 v[20:21], v[20:21], v[84:85], v[72:73]
	ds_read_b128 v[72:75], v67 offset:9280
	s_waitcnt lgkmcnt(1)
	v_mfma_f32_16x16x32_bf16 v[20:23], v[76:79], v[88:91], v[20:23]
	s_waitcnt lgkmcnt(0)
	v_mfma_f32_16x16x32_bf16 v[20:23], v[80:83], v[72:75], v[20:23]
	v_cvt_pk_bf16_f32 v72, v24, v25
	v_cvt_pk_bf16_f32 v73, v26, v27
	ds_write_b64 v63, v[72:73]
	s_nop 4
	v_cvt_pk_bf16_f32 v72, v20, v21
	v_cvt_pk_bf16_f32 v73, v22, v23
	ds_write_b64 v64, v[72:73]
	s_waitcnt lgkmcnt(0)
	s_barrier
	v_add3_u32 v72, s30, v51, v48
	s_waitcnt vmcnt(11)
	ds_write_b128 v72, v[32:35] offset:18432
	s_waitcnt vmcnt(10)
	ds_write_b128 v72, v[36:39] offset:27648
	s_waitcnt vmcnt(8)
	ds_write_b128 v72, v[40:43] offset:36864
	ds_write_b128 v72, v[44:47] offset:46080
	s_and_saveexec_b64 s[22:23], s[8:9]
	s_cbranch_execz .LBB0_437
	v_lshl_add_u32 v32, v134, 2, s30
	s_waitcnt vmcnt(7)
	ds_write_b128 v32, v[28:31] offset:55296
	s_branch .LBB0_437

; __device__ __forceinline__ void phase_out(const Params& p, unsigned char* shm) {
;     constexpr int LD = 72, TILE = 64 * LD, NPAIR = NCH * 8;
;     const int tid = threadIdx.x, lane = tid & 63, wid = tid >> 6, fr = lane & 15, fq = lane >> 4;
;     const int half = wid >> 2, nt = wid & 3, th = tid & 255, crow = th >> 3, cseg = (th & 7) * 8;
;     bf16_t* base = (bf16_t*)shm + half * 7 * TILE;
;     bf16_t* SbT = base; bf16_t* UTt = base + TILE; bf16_t* Qt = base + 2 * TILE; bf16_t* AQt = base + 3 * TILE; bf16_t* YVt = base + 4 * TILE; bf16_t* PVt = base + 5 * TILE; bf16_t* GBt = base + 6 * TILE;
;     u32x4 g[7][2];
;     auto gload = [&](int pr) {
;         const int item = 2 * pr + half, h = item & 15, row0 = (item >> 4) * 64; const size_t cb = (size_t)item * 4096;
; #pragma unroll
;         for (int i = 0; i < 2; ++i) { const int r = crow + 32 * i; const size_t o = cb + r * 64 + cseg;
;             g[0][i] = *(const u32x4*)(p.Z + (size_t)(row0 + r) * LDZ + ZC_S + h * 64 + cseg);
;             g[1][i] = *(const u32x4*)(p.UTG + o); g[2][i] = *(const u32x4*)(p.QG + o); g[3][i] = *(const u32x4*)(p.AQBG + o); g[4][i] = *(const u32x4*)(p.YVG + o);
;             g[5][i] = *(const u32x4*)(p.PV + ((size_t)(row0 + r) * 16 + h) * 64 + cseg);
;             g[6][i] = *(const u32x4*)(p.Z + (size_t)(row0 + r) * LDZ + ZC_GB + h * 64 + cseg); }
;     };
;     if ((int)blockIdx.x < NPAIR) gload(blockIdx.x);
;     for (int pr = blockIdx.x; pr < NPAIR; pr += gridDim.x) {
;         const int item = 2 * pr + half, h = item & 15, row0 = (item >> 4) * 64;
;         const float rk = p.PRK[(size_t)(row0 + 16 * nt + fr) * 16 + h];
;         f32x4 gng[4], gnb[4];
; #pragma unroll
;         for (int mv = 0; mv < 4; ++mv) { gng[mv] = *(const f32x4*)(p.gn_g + h * 64 + 16 * mv + 4 * fq); gnb[mv] = *(const f32x4*)(p.gn_b + h * 64 + 16 * mv + 4 * fq); }
; #pragma unroll
;         for (int a = 0; a < 7; ++a)
; #pragma unroll
;             for (int i = 0; i < 2; ++i) *(u32x4*)(base + a * TILE + (crow + 32 * i) * LD + cseg) = g[a][i];
;         { const int npr = pr + (int)gridDim.x; gload(npr < NPAIR ? npr : pr); }
.LBB0_496:
	s_or_b64 exec, exec, s[2:3]
	s_cmpk_gt_i32 s40, 0x10ff
	s_barrier
	s_cbranch_scc1 .LBB0_499
	s_load_dwordx2 s[2:3], s[0:1], 0xb8
	v_lshrrev_b32_e32 v109, 8, v133
	v_lshl_add_u32 v104, s40, 1, v109
	s_waitcnt vmcnt(2)
	v_lshlrev_b32_e32 v0, 2, v104
	v_and_b32_e32 v111, 31, v164
	v_and_b32_e32 v26, 0xffffffc0, v0
	v_or_b32_e32 v20, v26, v111
	s_movk_i32 s10, 0x3a00
	s_waitcnt lgkmcnt(0)
	v_mov_b64_e32 v[0:1], s[2:3]
	v_lshlrev_b32_e32 v2, 7, v104
	v_and_b32_e32 v56, 56, v131
	v_mov_b32_e32 v107, 0
	v_mad_i64_i32 v[0:1], s[4:5], v20, s10, v[0:1]
	v_and_b32_e32 v106, 0x780, v2
	v_lshlrev_b32_e32 v58, 1, v56
	v_mov_b32_e32 v59, v107
	v_lshl_add_u64 v[0:1], v[0:1], 0, v[106:107]
	v_lshl_add_u64 v[24:25], v[0:1], 0, v[58:59]
	s_movk_i32 s11, 0x1000
	v_add_co_u32_e32 v0, vcc, s11, v24
	v_ashrrev_i32_e32 v105, 31, v104
	s_nop 0
	v_addc_co_u32_e32 v1, vcc, 0, v25, vcc
	s_movk_i32 s20, 0x3000
	v_lshlrev_b64 v[32:33], 12, v[104:105]
	s_load_dwordx8 s[12:19], s[0:1], 0xe0
	v_add_co_u32_e32 v34, vcc, s20, v24
	v_or_b32_e32 v105, 32, v111
	s_nop 0
	v_addc_co_u32_e32 v35, vcc, 0, v25, vcc
	v_or_b32_e32 v48, v26, v105
	v_mov_b64_e32 v[24:25], s[2:3]
	s_load_dwordx2 s[4:5], s[0:1], 0x100
	s_load_dwordx2 s[6:7], s[0:1], 0x128
	v_mad_i64_i32 v[24:25], s[8:9], v48, s10, v[24:25]
	v_ashrrev_i32_e32 v21, 31, v20
	v_lshl_add_u64 v[24:25], v[24:25], 0, v[106:107]
	v_lshl_or_b32 v108, v111, 6, v56
	v_lshlrev_b64 v[20:21], 11, v[20:21]
	v_ashrrev_i32_e32 v49, 31, v48
	v_lshl_add_u64 v[52:53], v[24:25], 0, v[58:59]
	v_or_b32_e32 v4, v32, v108
	v_mov_b32_e32 v5, v33
	s_waitcnt lgkmcnt(0)
	v_lshl_add_u64 v[20:21], s[12:13], 0, v[20:21]
	v_lshl_or_b32 v110, v105, 6, v56
	v_add_co_u32_e32 v36, vcc, s11, v52
	v_lshlrev_b64 v[48:49], 11, v[48:49]
	v_lshlrev_b64 v[16:17], 1, v[4:5]
	v_lshl_add_u64 v[20:21], v[20:21], 0, v[106:107]
	v_or_b32_e32 v32, v32, v110
	v_addc_co_u32_e32 v37, vcc, 0, v53, vcc
	v_lshl_add_u64 v[48:49], s[12:13], 0, v[48:49]
	v_lshl_add_u64 v[4:5], s[4:5], 0, v[16:17]
	s_waitcnt vmcnt(0)
	v_lshl_add_u64 v[8:9], s[14:15], 0, v[16:17]
	v_lshl_add_u64 v[12:13], s[16:17], 0, v[16:17]
	v_lshl_add_u64 v[16:17], s[18:19], 0, v[16:17]
	v_lshl_add_u64 v[20:21], v[20:21], 0, v[58:59]
	v_lshlrev_b64 v[44:45], 1, v[32:33]
	v_lshl_add_u64 v[48:49], v[48:49], 0, v[106:107]
	v_add_co_u32_e32 v52, vcc, s20, v52
	global_load_dwordx4 v[0:3], v[0:1], off offset:2048
	v_lshl_add_u64 v[32:33], s[4:5], 0, v[44:45]
	global_load_dwordx4 v[4:7], v[4:5], off
	v_lshl_add_u64 v[40:41], s[16:17], 0, v[44:45]
	global_load_dwordx4 v[8:11], v[8:9], off
	v_lshl_add_u64 v[48:49], v[48:49], 0, v[58:59]
	global_load_dwordx4 v[12:15], v[12:13], off
	v_addc_co_u32_e32 v53, vcc, 0, v53, vcc
	global_load_dwordx4 v[16:19], v[16:17], off
	v_lshrrev_b32_e32 v60, 2, v133
	global_load_dwordx4 v[20:23], v[20:21], off
	s_nop 0
	global_load_dwordx4 v[24:27], v[34:35], off offset:256
	global_load_dwordx4 v[28:31], v[36:37], off offset:2048
	v_lshl_add_u64 v[36:37], s[14:15], 0, v[44:45]
	v_lshl_add_u64 v[44:45], s[18:19], 0, v[44:45]
	global_load_dwordx4 v[32:35], v[32:33], off
	s_load_dwordx4 s[24:27], s[0:1], 0x98
	global_load_dwordx4 v[36:39], v[36:37], off
	s_mov_b32 s8, 0xfc00
	global_load_dwordx4 v[40:43], v[40:41], off
	v_bfe_u32 v59, v133, 4, 2
	global_load_dwordx4 v[44:47], v[44:45], off
	v_and_or_b32 v119, v60, 48, v161
	global_load_dwordx4 v[48:51], v[48:49], off
	v_mad_u32_u24 v57, v109, s8, 0
	global_load_dwordx4 v[52:55], v[52:53], off offset:256
	v_mul_u32_u24_e32 v60, 0x90, v119
	v_lshlrev_b32_e32 v122, 3, v59
	v_lshlrev_b32_e32 v106, 4, v59
	v_add_u32_e32 v58, v57, v58
	v_add3_u32 v123, v57, v60, v122
	v_add_u32_e32 v57, v57, v106
	v_mul_u32_u24_e32 v59, 0x90, v111
	v_mul_u32_u24_e32 v60, 0x90, v161
	v_readlane_b32 s8, v244, 3
	s_waitcnt lgkmcnt(0)
	v_lshl_add_u64 v[112:113], s[24:25], 0, v[106:107]
	v_lshl_add_u64 v[114:115], s[26:27], 0, v[106:107]
	v_lshl_add_u32 v124, v109, 2, s8
	s_lshl_b32 s21, s38, 3
	s_lshl_b32 s22, s38, 1
	v_add_u32_e32 v125, v58, v59
	v_lshlrev_b32_e32 v116, 1, v56
	v_add_u32_e32 v126, v57, v60
	v_mov_b32_e32 v127, 0x3a27c5ac
	s_mov_b32 s23, 0x800000
	v_mbcnt_hi_u32_b32 v134, -1, v129
	s_mov_b32 s8, s40
	s_waitcnt vmcnt(0)
.LBB0_498:
	v_and_b32_e32 v135, 0xffffffc0, v124
	v_or_b32_e32 v56, v135, v119
	v_ashrrev_i32_e32 v57, 31, v56
	s_add_i32 s24, s8, s38
	v_and_b32_e32 v136, 15, v104
	v_lshlrev_b64 v[56:57], 6, v[56:57]
	s_cmpk_lt_i32 s24, 0x1100
	v_lshl_add_u64 v[56:57], s[6:7], 0, v[56:57]
	v_lshlrev_b32_e32 v106, 2, v136
	s_cselect_b64 s[26:27], -1, 0
	v_lshl_add_u64 v[56:57], v[56:57], 0, v[106:107]
	v_lshlrev_b32_e32 v106, 8, v136
	s_and_b64 vcc, s[26:27], exec
	global_load_dword v118, v[56:57], off
	v_lshl_add_u64 v[56:57], v[112:113], 0, v[106:107]
	v_lshl_add_u64 v[60:61], v[114:115], 0, v[106:107]
	s_cselect_b32 s8, s24, s8
	global_load_dwordx4 v[80:83], v[56:57], off
	global_load_dwordx4 v[84:87], v[60:61], off
	global_load_dwordx4 v[72:75], v[56:57], off offset:64
	global_load_dwordx4 v[76:79], v[60:61], off offset:64
	global_load_dwordx4 v[64:67], v[56:57], off offset:128
	global_load_dwordx4 v[68:71], v[60:61], off offset:128
	s_nop 0
	global_load_dwordx4 v[56:59], v[56:57], off offset:192
	s_nop 0
	global_load_dwordx4 v[60:63], v[60:61], off offset:192
	s_waitcnt vmcnt(24)
	ds_write_b128 v125, v[0:3]
	s_waitcnt vmcnt(17)
	ds_write_b128 v125, v[28:31] offset:4608
	ds_write_b128 v125, v[4:7] offset:9216
	s_waitcnt vmcnt(16)
	ds_write_b128 v125, v[32:35] offset:13824
	ds_write_b128 v125, v[8:11] offset:18432
	s_waitcnt vmcnt(15)
	ds_write_b128 v125, v[36:39] offset:23040
	ds_write_b128 v125, v[12:15] offset:27648
	s_waitcnt vmcnt(14)
; __device__ __forceinline__ f32x4 ld_bf4(const bf16_t* p) { const u32x2 u = *(const u32x2*)p; return (f32x4){bf_lo(u.x), bf_hi(u.x), bf_lo(u.y), bf_hi(u.y)}; }
; #define LDS_BARRIER() do { asm volatile("s_waitcnt lgkmcnt(0)" ::: "memory"); __builtin_amdgcn_s_barrier(); asm volatile("" ::: "memory"); } while (0)
; #define MFMA16(a, b, c) __builtin_amdgcn_mfma_f32_16x16x32_bf16(a, b, c, 0, 0, 0)
; __device__ __forceinline__ void phase_out(const Params& p, unsigned char* shm) {
;     ...
;         for (int a = 0; a < 7; ++a)
; #pragma unroll
;             for (int i = 0; i < 2; ++i) *(u32x4*)(base + a * TILE + (crow + 32 * i) * LD + cseg) = g[a][i];
;         { const int npr = pr + (int)gridDim.x; gload(npr < NPAIR ? npr : pr); }
;         LDS_BARRIER();
;         const int trow = 16 * nt + fr;
;         f32x4 acc[4];
; #pragma unroll
;         for (int mv = 0; mv < 4; ++mv) acc[mv] = ld_bf4(YVt + trow * LD + 16 * mv + 4 * fq);
; #pragma unroll
;         for (int ks = 0; ks < 2; ++ks) {
;             const bf16x8 bq = ldfrag(Qt, LD, 16 * nt, 32 * ks, fr, fq), ba = ldfrag(AQt, LD, 16 * nt, 32 * ks, fr, fq);
; #pragma unroll
;             for (int mv = 0; mv < 4; ++mv) {
;                 acc[mv] = MFMA16(ldfrag(SbT, LD, 16 * mv, 32 * ks, fr, fq), bq, acc[mv]);
;                 acc[mv] = MFMA16(ldfrag(UTt, LD, 16 * mv, 32 * ks, fr, fq), ba, acc[mv]);
;             }
;         }
	ds_write_b128 v125, v[40:43] offset:32256
	ds_write_b128 v125, v[16:19] offset:36864
	s_waitcnt vmcnt(13)
	ds_write_b128 v125, v[44:47] offset:41472
	ds_write_b128 v125, v[20:23] offset:46080
	s_waitcnt vmcnt(12)
	ds_write_b128 v125, v[48:51] offset:50688
	ds_write_b128 v125, v[24:27] offset:55296
	s_waitcnt vmcnt(11)
	ds_write_b128 v125, v[52:55] offset:59904
	v_lshl_add_u32 v0, s8, 1, v109
	v_lshlrev_b32_e32 v1, 2, v0
	v_and_b32_e32 v30, 0xffffffc0, v1
	v_ashrrev_i32_e32 v1, 31, v0
	v_lshlrev_b64 v[32:33], 12, v[0:1]
	v_or_b32_e32 v20, v30, v111
	v_mov_b64_e32 v[28:29], s[2:3]
	v_lshlrev_b32_e32 v0, 7, v0
	v_mad_i64_i32 v[2:3], s[8:9], v20, s10, v[28:29]
	v_and_b32_e32 v106, 0x780, v0
	v_mov_b32_e32 v117, v107
	v_lshl_add_u64 v[0:1], v[2:3], 0, v[106:107]
	v_lshl_add_u64 v[24:25], v[0:1], 0, v[116:117]
	v_add_co_u32_e64 v0, s[8:9], s11, v24
	v_or_b32_e32 v48, v30, v105
	s_nop 0
	v_addc_co_u32_e64 v1, s[8:9], 0, v25, s[8:9]
	v_add_co_u32_e64 v24, s[8:9], s20, v24
	v_ashrrev_i32_e32 v21, 31, v20
	s_nop 0
	v_addc_co_u32_e64 v25, s[8:9], 0, v25, s[8:9]
	v_mad_i64_i32 v[28:29], s[8:9], v48, s10, v[28:29]
	v_lshl_add_u64 v[28:29], v[28:29], 0, v[106:107]
	v_ashrrev_i32_e32 v49, 31, v48
	v_lshl_add_u64 v[52:53], v[28:29], 0, v[116:117]
	v_lshlrev_b64 v[20:21], 11, v[20:21]
	v_add_co_u32_e64 v28, s[8:9], s11, v52
	v_lshlrev_b64 v[48:49], 11, v[48:49]
	v_or_b32_e32 v4, v32, v108
	v_mov_b32_e32 v5, v33
	v_lshl_add_u64 v[20:21], s[12:13], 0, v[20:21]
	v_or_b32_e32 v32, v32, v110
	v_addc_co_u32_e64 v29, s[8:9], 0, v53, s[8:9]
	v_lshl_add_u64 v[48:49], s[12:13], 0, v[48:49]
	v_lshlrev_b64 v[16:17], 1, v[4:5]
	v_lshl_add_u64 v[20:21], v[20:21], 0, v[106:107]
	v_lshlrev_b64 v[44:45], 1, v[32:33]
	v_lshl_add_u64 v[48:49], v[48:49], 0, v[106:107]
	v_add_co_u32_e64 v52, s[8:9], s20, v52
	v_lshl_add_u64 v[4:5], s[4:5], 0, v[16:17]
	v_lshl_add_u64 v[8:9], s[14:15], 0, v[16:17]
	v_lshl_add_u64 v[12:13], s[16:17], 0, v[16:17]
	v_lshl_add_u64 v[16:17], s[18:19], 0, v[16:17]
	v_lshl_add_u64 v[20:21], v[20:21], 0, v[116:117]
	v_lshl_add_u64 v[32:33], s[4:5], 0, v[44:45]
	v_lshl_add_u64 v[36:37], s[14:15], 0, v[44:45]
	v_lshl_add_u64 v[40:41], s[16:17], 0, v[44:45]
	v_lshl_add_u64 v[44:45], s[18:19], 0, v[44:45]
	v_lshl_add_u64 v[48:49], v[48:49], 0, v[116:117]
	v_addc_co_u32_e64 v53, s[8:9], 0, v53, s[8:9]
	global_load_dwordx4 v[0:3], v[0:1], off offset:2048
	v_add_u32_e32 v106, 0x9000, v123
	global_load_dwordx4 v[4:7], v[4:5], off
	v_add_u32_e32 v120, v123, v122
	global_load_dwordx4 v[8:11], v[8:9], off
	v_and_b32_e32 v137, 64, v134
	global_load_dwordx4 v[12:15], v[12:13], off
	v_add_u32_e32 v137, 64, v137
	global_load_dwordx4 v[16:19], v[16:17], off
	v_add_u32_e32 v124, s21, v124
	global_load_dwordx4 v[20:23], v[20:21], off
	v_add_u32_e32 v104, s22, v104
	global_load_dwordx4 v[24:27], v[24:25], off offset:256
	s_nop 0
	global_load_dwordx4 v[28:31], v[28:29], off offset:2048
	s_nop 0
	global_load_dwordx4 v[32:35], v[32:33], off
	s_nop 0
	global_load_dwordx4 v[36:39], v[36:37], off
	s_nop 0
	global_load_dwordx4 v[40:43], v[40:41], off
	s_nop 0
	global_load_dwordx4 v[44:47], v[44:45], off
	s_nop 0
	global_load_dwordx4 v[48:51], v[48:49], off
	s_nop 0
	global_load_dwordx4 v[52:55], v[52:53], off offset:256
	s_waitcnt lgkmcnt(0)
	s_barrier
	ds_read2_b64 v[88:91], v106 offset1:4
	ds_read2_b64 v[96:99], v106 offset0:8 offset1:12
	ds_read_b128 v[138:141], v120 offset:18432
	ds_read_b128 v[142:145], v120 offset:27648
	ds_read_b128 v[146:149], v126
	s_waitcnt lgkmcnt(4)
	v_lshlrev_b32_e32 v92, 16, v88
	v_and_b32_e32 v93, 0xffff0000, v88
	v_lshlrev_b32_e32 v94, 16, v89
	v_and_b32_e32 v95, 0xffff0000, v89
	v_lshlrev_b32_e32 v88, 16, v90
	v_and_b32_e32 v89, 0xffff0000, v90
	s_waitcnt lgkmcnt(0)
	v_mfma_f32_16x16x32_bf16 v[92:95], v[146:149], v[138:141], v[92:95]
	ds_read_b128 v[146:149], v126 offset:9216
	v_lshlrev_b32_e32 v90, 16, v91
	v_and_b32_e32 v91, 0xffff0000, v91
	s_waitcnt lgkmcnt(0)
	v_mfma_f32_16x16x32_bf16 v[92:95], v[146:149], v[142:145], v[92:95]
	ds_read_b128 v[146:149], v126 offset:2304
	v_lshlrev_b32_e32 v100, 16, v96
	v_and_b32_e32 v101, 0xffff0000, v96
	s_waitcnt lgkmcnt(0)
	v_mfma_f32_16x16x32_bf16 v[88:91], v[146:149], v[138:141], v[88:91]
	ds_read_b128 v[146:149], v126 offset:11520
	v_lshlrev_b32_e32 v102, 16, v97
	v_and_b32_e32 v103, 0xffff0000, v97
	s_waitcnt lgkmcnt(0)
	v_mfma_f32_16x16x32_bf16 v[88:91], v[146:149], v[142:145], v[88:91]
	ds_read_b128 v[146:149], v126 offset:4608
	v_lshlrev_b32_e32 v96, 16, v98
	v_and_b32_e32 v97, 0xffff0000, v98
	s_waitcnt lgkmcnt(0)
	v_mfma_f32_16x16x32_bf16 v[100:103], v[146:149], v[138:141], v[100:103]
	ds_read_b128 v[146:149], v126 offset:13824
	v_lshlrev_b32_e32 v98, 16, v99
	v_and_b32_e32 v99, 0xffff0000, v99
	s_waitcnt lgkmcnt(0)
	v_mfma_f32_16x16x32_bf16 v[146:149], v[146:149], v[142:145], v[100:103]
	s_nop 2
	ds_read_b128 v[100:103], v126 offset:6912
	s_waitcnt lgkmcnt(0)
	v_mfma_f32_16x16x32_bf16 v[96:99], v[100:103], v[138:141], v[96:99]
	ds_read_b128 v[100:103], v126 offset:16128
	s_waitcnt lgkmcnt(0)
	v_mfma_f32_16x16x32_bf16 v[138:141], v[100:103], v[142:145], v[96:99]
	ds_read_b128 v[142:145], v120 offset:18496
	ds_read_b128 v[150:153], v120 offset:27712
	s_nop 2
	ds_read_b128 v[96:99], v126 offset:64
	s_waitcnt lgkmcnt(0)
	v_mfma_f32_16x16x32_bf16 v[92:95], v[96:99], v[142:145], v[92:95]
	ds_read_b128 v[96:99], v126 offset:9280
	s_waitcnt lgkmcnt(0)
	v_mfma_f32_16x16x32_bf16 v[100:103], v[96:99], v[150:153], v[92:95]
	s_nop 4
	ds_read_b128 v[92:95], v126 offset:2368
	s_nop 1
	v_mov_b32_e32 v120, v101
	s_waitcnt lgkmcnt(0)
; __device__ __forceinline__ float silu_f(float x) { return x * __builtin_amdgcn_rcpf(1.0f + __builtin_amdgcn_exp2f(-1.44269504089f * x)); }
; __device__ __forceinline__ f32x4 ld_bf4(const bf16_t* p) { const u32x2 u = *(const u32x2*)p; return (f32x4){bf_lo(u.x), bf_hi(u.x), bf_lo(u.y), bf_hi(u.y)}; }
; __device__ __forceinline__ void st_bf4(bf16_t* p, f32x4 v) { u32x2 u; u.x = pk_bf16(v[0], v[1]); u.y = pk_bf16(v[2], v[3]); *(u32x2*)p = u; }
; __device__ __forceinline__ void phase_out(const Params& p, unsigned char* shm) {
;     ...
;         float s = 0.f;
; #pragma unroll
;         for (int mv = 0; mv < 4; ++mv) s += (acc[mv][0] + acc[mv][1]) + (acc[mv][2] + acc[mv][3]);
;         s += __shfl_xor(s, 16); s += __shfl_xor(s, 32);
;         const float mean = s * (1.0f / 64.0f);
;         float q = 0.f;
; #pragma unroll
;         for (int mv = 0; mv < 4; ++mv) { const f32x4 d = acc[mv] - mean; q += (d[0] * d[0] + d[1] * d[1]) + (d[2] * d[2] + d[3] * d[3]); }
;         q += __shfl_xor(q, 16); q += __shfl_xor(q, 32);
;         const float rstd = rsqrtf(q * (1.0f / 64.0f) + 64e-5f);
; #pragma unroll
;         for (int mv = 0; mv < 4; ++mv) {
;             const int vch = 16 * mv + 4 * fq;
;             const f32x4 vmx = ld_bf4(PVt + trow * LD + vch), gb = ld_bf4(GBt + trow * LD + vch);
;             f32x4 o = (acc[mv] - mean) * rstd * gng[mv] + gnb[mv] + rk * vmx;
; #pragma unroll
;             for (int e = 0; e < 4; ++e) o[e] *= silu_f(gb[e]);
;             st_bf4(YVt + trow * LD + vch, o);
	v_mfma_f32_16x16x32_bf16 v[88:91], v[92:95], v[142:145], v[88:91]
	ds_read_b128 v[92:95], v126 offset:11584
	v_mov_b32_e32 v121, v102
	s_waitcnt lgkmcnt(0)
	v_mfma_f32_16x16x32_bf16 v[96:99], v[92:95], v[150:153], v[88:91]
	s_nop 3
	ds_read_b128 v[88:91], v126 offset:4672
	ds_read_b128 v[92:95], v126 offset:13888
	s_waitcnt lgkmcnt(1)
	v_mfma_f32_16x16x32_bf16 v[88:91], v[88:91], v[142:145], v[146:149]
	s_waitcnt lgkmcnt(0)
	v_mfma_f32_16x16x32_bf16 v[92:95], v[92:95], v[150:153], v[88:91]
	s_nop 5
	ds_read_b128 v[88:91], v126 offset:6976
	s_waitcnt lgkmcnt(0)
	v_mfma_f32_16x16x32_bf16 v[88:91], v[88:91], v[142:145], v[138:141]
	s_nop 2
	ds_read_b128 v[138:141], v126 offset:16192
	v_add_f32_e32 v142, v94, v95
	s_waitcnt lgkmcnt(0)
	v_mfma_f32_16x16x32_bf16 v[88:91], v[138:141], v[150:153], v[88:91]
	v_mov_b32_e32 v138, v100
	v_mov_b32_e32 v139, v103
	v_pk_add_f32 v[120:121], v[120:121], v[138:139]
	v_mov_b32_e32 v138, v97
	v_mov_b32_e32 v139, v98
	v_mov_b32_e32 v140, v96
	v_mov_b32_e32 v141, v99
	v_pk_add_f32 v[138:139], v[138:139], v[140:141]
	v_add_f32_e32 v120, v120, v121
	v_pk_add_f32 v[138:139], v[138:139], v[138:139] op_sel:[0,1] op_sel_hi:[1,0]
	v_add_f32_e32 v120, 0, v120
	v_add_f32_e32 v140, v92, v93
	v_mov_b32_e32 v121, v88
	v_mov_b32_e32 v139, v89
	v_mov_b32_e32 v141, v90
	v_mov_b32_e32 v143, v91
	v_pk_add_f32 v[120:121], v[120:121], v[138:139]
	v_pk_add_f32 v[138:139], v[140:141], v[142:143]
	s_nop 0
	v_pk_add_f32 v[120:121], v[120:121], v[138:139]
	s_nop 0
	v_add_f32_e32 v120, v120, v121
	v_xor_b32_e32 v121, 16, v134
	v_cmp_lt_i32_e64 s[8:9], v121, v137
	s_nop 1
	v_cndmask_b32_e64 v121, v134, v121, s[8:9]
	v_lshlrev_b32_e32 v144, 2, v121
	ds_bpermute_b32 v121, v144, v120
	s_waitcnt lgkmcnt(0)
	v_add_f32_e32 v120, v120, v121
	v_xor_b32_e32 v121, 32, v134
	v_cmp_lt_i32_e64 s[8:9], v121, v137
	s_nop 1
	v_cndmask_b32_e64 v121, v134, v121, s[8:9]
	v_lshlrev_b32_e32 v137, 2, v121
	ds_bpermute_b32 v121, v137, v120
	s_waitcnt lgkmcnt(0)
	v_add_f32_e32 v145, v120, v121
	v_fmamk_f32 v121, v145, 0xbc800000, v101
	v_fmamk_f32 v120, v145, 0xbc800000, v100
	v_fmamk_f32 v103, v145, 0xbc800000, v103
	v_fmac_f32_e32 v102, 0xbc800000, v145
	v_pk_mul_f32 v[100:101], v[102:103], v[102:103]
	v_pk_mul_f32 v[138:139], v[120:121], v[120:121]
	v_fmamk_f32 v99, v145, 0xbc800000, v99
	v_pk_mov_b32 v[140:141], v[138:139], v[100:101] op_sel:[1,0]
	v_mov_b32_e32 v139, v101
	v_pk_add_f32 v[100:101], v[140:141], v[138:139]
	v_fmac_f32_e32 v98, 0xbc800000, v145
	v_pk_add_f32 v[138:139], v[100:101], v[100:101] op_sel_hi:[0,1]
	v_fmamk_f32 v101, v145, 0xbc800000, v97
	v_fmamk_f32 v100, v145, 0xbc800000, v96
	v_pk_mul_f32 v[96:97], v[98:99], v[98:99]
	v_pk_mul_f32 v[140:141], v[100:101], v[100:101]
	v_fmac_f32_e32 v94, 0xbc800000, v145
	v_pk_mov_b32 v[142:143], v[140:141], v[96:97] op_sel:[1,0]
	v_mov_b32_e32 v141, v97
	v_pk_add_f32 v[96:97], v[142:143], v[140:141]
	v_fmamk_f32 v95, v145, 0xbc800000, v95
	v_pk_add_f32 v[140:141], v[96:97], v[96:97] op_sel_hi:[0,1]
	v_fmamk_f32 v96, v145, 0xbc800000, v92
	v_fmamk_f32 v97, v145, 0xbc800000, v93
	v_mul_f32_e32 v92, v96, v96
	v_pk_fma_f32 v[92:93], v[96:97], v[96:97], v[92:93] op_sel_hi:[1,1,0]
	v_fmamk_f32 v91, v145, 0xbc800000, v91
	v_mul_f32_e32 v92, v94, v94
	v_pk_fma_f32 v[142:143], v[94:95], v[94:95], v[92:93] op_sel_hi:[1,1,0]
	v_fmamk_f32 v90, v145, 0xbc800000, v90
	v_fmamk_f32 v89, v145, 0xbc800000, v89
	v_fmac_f32_e32 v88, 0xbc800000, v145
	v_mul_f32_e32 v92, v88, v88
	v_mul_f32_e32 v142, v89, v89
	v_mul_f32_e32 v138, v90, v90
	v_mul_f32_e32 v140, v91, v91
	v_pk_add_f32 v[92:93], v[92:93], v[142:143]
	v_pk_add_f32 v[138:139], v[138:139], v[140:141]
	s_nop 0
	v_pk_add_f32 v[92:93], v[92:93], v[138:139]
	s_nop 0
	v_add_f32_e32 v92, v92, v93
	ds_bpermute_b32 v93, v144, v92
	s_waitcnt lgkmcnt(0)
	v_add_f32_e32 v92, v92, v93
	ds_bpermute_b32 v93, v137, v92
	v_add_u32_e32 v137, 0xd800, v123
	ds_read2_b64 v[142:145], v137 offset1:4
	s_waitcnt lgkmcnt(1)
	v_add_f32_e32 v92, v92, v93
	v_fmamk_f32 v92, v92, 0x3c800000, v127
	v_cmp_gt_f32_e64 s[8:9], s23, v92
	v_mul_f32_e32 v93, 0x4b800000, v92
	s_nop 0
	v_cndmask_b32_e64 v92, v92, v93, s[8:9]
	v_rsq_f32_e32 v92, v92
	s_nop 0
	v_mul_f32_e32 v93, 0x45800000, v92
	v_cndmask_b32_e64 v92, v92, v93, s[8:9]
	v_add_u32_e32 v93, 0xb000, v123
	v_pk_mul_f32 v[120:121], v[120:121], v[92:93] op_sel_hi:[1,0]
	v_pk_mul_f32 v[102:103], v[102:103], v[92:93] op_sel_hi:[1,0]
	s_waitcnt vmcnt(20)
	v_pk_fma_f32 v[80:81], v[80:81], v[120:121], v[84:85]
	s_waitcnt lgkmcnt(0)
	v_lshlrev_b32_e32 v84, 16, v142
	v_and_b32_e32 v85, 0xffff0000, v142
	v_pk_fma_f32 v[82:83], v[82:83], v[102:103], v[86:87]
	v_mul_f32_e32 v86, 0xbfb8aa3b, v84
	v_mul_f32_e32 v87, 0xbfb8aa3b, v85
	v_exp_f32_e32 v86, v86
	v_exp_f32_e32 v87, v87
	ds_read2_b64 v[138:141], v93 offset0:128 offset1:132
	v_pk_mul_f32 v[100:101], v[100:101], v[92:93] op_sel_hi:[1,0]
	v_add_f32_e32 v86, 1.0, v86
	v_add_f32_e32 v87, 1.0, v87
	v_rcp_f32_e32 v86, v86
	v_rcp_f32_e32 v87, v87
	s_waitcnt lgkmcnt(0)
	v_lshlrev_b32_e32 v146, 16, v138
	v_and_b32_e32 v147, 0xffff0000, v138
	v_pk_fma_f32 v[80:81], v[118:119], v[146:147], v[80:81] op_sel_hi:[0,1,1]
	v_pk_mul_f32 v[84:85], v[86:87], v[84:85]
	v_pk_mul_f32 v[98:99], v[98:99], v[92:93] op_sel_hi:[1,0]
	v_pk_mul_f32 v[80:81], v[84:85], v[80:81]
	v_lshlrev_b32_e32 v84, 16, v143
	v_and_b32_e32 v85, 0xffff0000, v143
	v_mul_f32_e32 v86, 0xbfb8aa3b, v84
	v_mul_f32_e32 v87, 0xbfb8aa3b, v85
	s_waitcnt vmcnt(18)
; __device__ __forceinline__ float silu_f(float x) { return x * __builtin_amdgcn_rcpf(1.0f + __builtin_amdgcn_exp2f(-1.44269504089f * x)); }
; __device__ __forceinline__ f32x4 ld_bf4(const bf16_t* p) { const u32x2 u = *(const u32x2*)p; return (f32x4){bf_lo(u.x), bf_hi(u.x), bf_lo(u.y), bf_hi(u.y)}; }
; __device__ __forceinline__ void st_bf4(bf16_t* p, f32x4 v) { u32x2 u; u.x = pk_bf16(v[0], v[1]); u.y = pk_bf16(v[2], v[3]); *(u32x2*)p = u; }
; #define LDS_BARRIER() do { asm volatile("s_waitcnt lgkmcnt(0)" ::: "memory"); __builtin_amdgcn_s_barrier(); asm volatile("" ::: "memory"); } while (0)
; __device__ __forceinline__ void phase_out(const Params& p, unsigned char* shm) {
;     ...
; #pragma unroll
;         for (int mv = 0; mv < 4; ++mv) {
;             const int vch = 16 * mv + 4 * fq;
;             const f32x4 vmx = ld_bf4(PVt + trow * LD + vch), gb = ld_bf4(GBt + trow * LD + vch);
;             f32x4 o = (acc[mv] - mean) * rstd * gng[mv] + gnb[mv] + rk * vmx;
; #pragma unroll
;             for (int e = 0; e < 4; ++e) o[e] *= silu_f(gb[e]);
;             st_bf4(YVt + trow * LD + vch, o);
;         }
;         LDS_BARRIER();
; #pragma unroll
;         for (int i = 0; i < 2; ++i) { const int r = crow + 32 * i; *(u32x4*)(p.ACT + (size_t)(row0 + r) * DM + 1024 + h * 64 + cseg) = *(const u32x4*)(YVt + r * LD + cseg); }
;         LDS_BARRIER();
	v_pk_fma_f32 v[72:73], v[72:73], v[100:101], v[76:77]
	v_lshlrev_b32_e32 v76, 16, v144
	v_and_b32_e32 v77, 0xffff0000, v144
	v_exp_f32_e32 v86, v86
	v_exp_f32_e32 v87, v87
	v_pk_fma_f32 v[74:75], v[74:75], v[98:99], v[78:79]
	v_mul_f32_e32 v78, 0xbfb8aa3b, v76
	v_mul_f32_e32 v79, 0xbfb8aa3b, v77
	v_exp_f32_e32 v78, v78
	v_exp_f32_e32 v79, v79
	v_add_f32_e32 v86, 1.0, v86
	v_add_f32_e32 v87, 1.0, v87
	v_rcp_f32_e32 v86, v86
	v_rcp_f32_e32 v87, v87
	v_add_f32_e32 v78, 1.0, v78
	v_add_f32_e32 v79, 1.0, v79
	v_rcp_f32_e32 v78, v78
	v_rcp_f32_e32 v79, v79
	v_pk_mul_f32 v[84:85], v[86:87], v[84:85]
	v_lshlrev_b32_e32 v86, 16, v140
	v_and_b32_e32 v87, 0xffff0000, v140
	v_pk_fma_f32 v[72:73], v[118:119], v[86:87], v[72:73] op_sel_hi:[0,1,1]
	v_pk_mul_f32 v[76:77], v[78:79], v[76:77]
	v_lshlrev_b32_e32 v138, 16, v139
	v_pk_mul_f32 v[72:73], v[76:77], v[72:73]
	v_lshlrev_b32_e32 v76, 16, v145
	v_and_b32_e32 v77, 0xffff0000, v145
	v_mul_f32_e32 v78, 0xbfb8aa3b, v76
	v_mul_f32_e32 v79, 0xbfb8aa3b, v77
	v_exp_f32_e32 v78, v78
	v_exp_f32_e32 v79, v79
	v_and_b32_e32 v139, 0xffff0000, v139
	v_lshlrev_b32_e32 v102, 16, v141
	v_add_f32_e32 v78, 1.0, v78
	v_add_f32_e32 v79, 1.0, v79
	v_rcp_f32_e32 v78, v78
	v_rcp_f32_e32 v79, v79
	v_and_b32_e32 v103, 0xffff0000, v141
	v_pk_fma_f32 v[82:83], v[118:119], v[138:139], v[82:83] op_sel_hi:[0,1,1]
	v_pk_fma_f32 v[74:75], v[118:119], v[102:103], v[74:75] op_sel_hi:[0,1,1]
	v_pk_mul_f32 v[76:77], v[78:79], v[76:77]
	v_pk_mul_f32 v[82:83], v[84:85], v[82:83]
	v_pk_mul_f32 v[74:75], v[76:77], v[74:75]
	v_cvt_pk_bf16_f32 v84, v80, v81
	v_cvt_pk_bf16_f32 v85, v82, v83
	v_cvt_pk_bf16_f32 v72, v72, v73
	v_cvt_pk_bf16_f32 v73, v74, v75
	ds_read2_b64 v[80:83], v93 offset0:136 offset1:140
	ds_write2_b64 v106, v[84:85], v[72:73] offset1:4
	ds_read2_b64 v[72:75], v137 offset0:8 offset1:12
	v_pk_mul_f32 v[84:85], v[96:97], v[92:93] op_sel_hi:[1,0]
	s_waitcnt lgkmcnt(2)
	v_lshlrev_b32_e32 v76, 16, v80
	v_and_b32_e32 v77, 0xffff0000, v80
	v_lshlrev_b32_e32 v78, 16, v81
	v_and_b32_e32 v79, 0xffff0000, v81
	v_pk_mul_f32 v[80:81], v[94:95], v[92:93] op_sel_hi:[1,0]
	s_waitcnt vmcnt(16)
	v_pk_fma_f32 v[64:65], v[64:65], v[84:85], v[68:69]
	s_waitcnt lgkmcnt(0)
	v_lshlrev_b32_e32 v68, 16, v72
	v_and_b32_e32 v69, 0xffff0000, v72
	v_pk_fma_f32 v[66:67], v[66:67], v[80:81], v[70:71]
	v_mul_f32_e32 v70, 0xbfb8aa3b, v68
	v_mul_f32_e32 v71, 0xbfb8aa3b, v69
	v_exp_f32_e32 v70, v70
	v_exp_f32_e32 v71, v71
	v_pk_fma_f32 v[64:65], v[118:119], v[76:77], v[64:65] op_sel_hi:[0,1,1]
	v_pk_fma_f32 v[66:67], v[118:119], v[78:79], v[66:67] op_sel_hi:[0,1,1]
	v_add_f32_e32 v70, 1.0, v70
	v_add_f32_e32 v71, 1.0, v71
	v_rcp_f32_e32 v70, v70
	v_rcp_f32_e32 v71, v71
	s_nop 0
	v_pk_mul_f32 v[68:69], v[70:71], v[68:69]
	s_nop 0
	v_pk_mul_f32 v[64:65], v[68:69], v[64:65]
	v_lshlrev_b32_e32 v68, 16, v73
	v_and_b32_e32 v69, 0xffff0000, v73
	v_mul_f32_e32 v70, 0xbfb8aa3b, v68
	v_mul_f32_e32 v71, 0xbfb8aa3b, v69
	v_exp_f32_e32 v70, v70
	v_exp_f32_e32 v71, v71
	v_pk_mul_f32 v[72:73], v[88:89], v[92:93] op_sel_hi:[1,0]
	v_cvt_pk_bf16_f32 v64, v64, v65
	v_add_f32_e32 v70, 1.0, v70
	v_add_f32_e32 v71, 1.0, v71
	v_rcp_f32_e32 v70, v70
	v_rcp_f32_e32 v71, v71
	s_waitcnt vmcnt(14)
	v_pk_fma_f32 v[56:57], v[56:57], v[72:73], v[60:61]
	v_lshlrev_b32_e32 v60, 16, v74
	v_and_b32_e32 v61, 0xffff0000, v74
	v_pk_mul_f32 v[68:69], v[70:71], v[68:69]
	v_pk_mul_f32 v[70:71], v[90:91], v[92:93] op_sel_hi:[1,0]
	v_pk_mul_f32 v[66:67], v[68:69], v[66:67]
	v_pk_fma_f32 v[58:59], v[58:59], v[70:71], v[62:63]
	v_mul_f32_e32 v62, 0xbfb8aa3b, v60
	v_mul_f32_e32 v63, 0xbfb8aa3b, v61
	v_exp_f32_e32 v62, v62
	v_exp_f32_e32 v63, v63
	v_cvt_pk_bf16_f32 v65, v66, v67
	v_lshlrev_b32_e32 v66, 16, v82
	v_add_f32_e32 v62, 1.0, v62
	v_add_f32_e32 v63, 1.0, v63
	v_rcp_f32_e32 v62, v62
	v_rcp_f32_e32 v63, v63
	v_and_b32_e32 v67, 0xffff0000, v82
	v_pk_fma_f32 v[56:57], v[118:119], v[66:67], v[56:57] op_sel_hi:[0,1,1]
	v_lshlrev_b32_e32 v68, 16, v83
	v_pk_mul_f32 v[60:61], v[62:63], v[60:61]
	v_and_b32_e32 v69, 0xffff0000, v83
	v_pk_mul_f32 v[56:57], v[60:61], v[56:57]
	v_lshlrev_b32_e32 v60, 16, v75
	v_and_b32_e32 v61, 0xffff0000, v75
	v_mul_f32_e32 v62, 0xbfb8aa3b, v60
	v_mul_f32_e32 v63, 0xbfb8aa3b, v61
	v_exp_f32_e32 v62, v62
	v_exp_f32_e32 v63, v63
	v_pk_fma_f32 v[58:59], v[118:119], v[68:69], v[58:59] op_sel_hi:[0,1,1]
	v_cvt_pk_bf16_f32 v56, v56, v57
	v_add_f32_e32 v62, 1.0, v62
	v_add_f32_e32 v63, 1.0, v63
	v_rcp_f32_e32 v62, v62
	v_rcp_f32_e32 v63, v63
	s_nop 0
	v_pk_mul_f32 v[60:61], v[62:63], v[60:61]
	s_nop 0
	v_pk_mul_f32 v[58:59], v[60:61], v[58:59]
	v_or_b32_e32 v60, v135, v111
	v_cvt_pk_bf16_f32 v57, v58, v59
	ds_write2_b64 v106, v[64:65], v[56:57] offset0:8 offset1:12
	s_waitcnt lgkmcnt(0)
	s_barrier
	s_load_dwordx2 s[8:9], s[0:1], 0xc8
	ds_read_b128 v[56:59], v125 offset:36864
	v_ashrrev_i32_e32 v61, 31, v60
	v_lshlrev_b64 v[60:61], 12, v[60:61]
	v_lshlrev_b32_e32 v106, 7, v136
	s_waitcnt lgkmcnt(0)
	v_lshl_add_u64 v[60:61], s[8:9], 0, v[60:61]
	v_lshl_add_u64 v[60:61], v[60:61], 0, v[106:107]
	v_lshl_add_u64 v[60:61], v[60:61], 0, v[116:117]
	global_store_dwordx4 v[60:61], v[56:59], off offset:2048
	v_or_b32_e32 v60, v135, v105
	ds_read_b128 v[56:59], v125 offset:41472
	v_ashrrev_i32_e32 v61, 31, v60
	v_lshlrev_b64 v[60:61], 12, v[60:61]
	v_lshl_add_u64 v[60:61], s[8:9], 0, v[60:61]
	v_lshl_add_u64 v[60:61], v[60:61], 0, v[106:107]
	v_lshl_add_u64 v[60:61], v[60:61], 0, v[116:117]
	s_waitcnt lgkmcnt(0)
	global_store_dwordx4 v[60:61], v[56:59], off offset:2048
	s_waitcnt lgkmcnt(0)
	s_barrier
	s_mov_b32 s8, s24
	s_cbranch_vccnz .LBB0_498

; __global__ __launch_bounds__(512, 2) void k_mega(Params p) {
;     extern __shared__ __attribute__((aligned(16))) unsigned char shm[];
	.amdhsa_kernel _Z6k_mega6Params
		.amdhsa_group_segment_fixed_size 0
		.amdhsa_private_segment_fixed_size 0
		.amdhsa_kernarg_size 576
		.amdhsa_user_sgpr_count 2
		.amdhsa_user_sgpr_dispatch_ptr 0
		.amdhsa_user_sgpr_queue_ptr 0
		.amdhsa_user_sgpr_kernarg_segment_ptr 1
		.amdhsa_user_sgpr_dispatch_id 0
		.amdhsa_user_sgpr_kernarg_preload_length 0
		.amdhsa_user_sgpr_kernarg_preload_offset 0
		.amdhsa_user_sgpr_private_segment_size 0
		.amdhsa_uses_dynamic_stack 0
		.amdhsa_enable_private_segment 0
		.amdhsa_system_sgpr_workgroup_id_x 1
		.amdhsa_system_sgpr_workgroup_id_y 0
		.amdhsa_system_sgpr_workgroup_id_z 0
		.amdhsa_system_sgpr_workgroup_info 0
		.amdhsa_system_vgpr_workitem_id 2
		.amdhsa_next_free_vgpr 245
		.amdhsa_next_free_sgpr 102
		.amdhsa_accum_offset 248
		.amdhsa_reserve_vcc 1
		.amdhsa_float_round_mode_32 0
		.amdhsa_float_round_mode_16_64 0
		.amdhsa_float_denorm_mode_32 3
		.amdhsa_float_denorm_mode_16_64 3
		.amdhsa_dx10_clamp 1
		.amdhsa_ieee_mode 1
		.amdhsa_fp16_overflow 0
		.amdhsa_tg_split 0
		.amdhsa_exception_fp_ieee_invalid_op 0
		.amdhsa_exception_fp_denorm_src 0
		.amdhsa_exception_fp_ieee_div_zero 0
		.amdhsa_exception_fp_ieee_overflow 0
		.amdhsa_exception_fp_ieee_underflow 0
		.amdhsa_exception_fp_ieee_inexact 0
		.amdhsa_exception_int_div_zero 0
	.end_amdhsa_kernel

; __global__ __launch_bounds__(512, 2) void k_mega(Params p) {
;     extern __shared__ __attribute__((aligned(16))) unsigned char shm[];
amdhsa.kernels:
  - .agpr_count:     0
    .args:
      - .offset:         0
        .size:           320
        .value_kind:     by_value
      - .offset:         320
        .size:           4
        .value_kind:     hidden_block_count_x
      - .offset:         324
        .size:           4
        .value_kind:     hidden_block_count_y
      - .offset:         328
        .size:           4
        .value_kind:     hidden_block_count_z
      - .offset:         332
        .size:           2
        .value_kind:     hidden_group_size_x
      - .offset:         334
        .size:           2
        .value_kind:     hidden_group_size_y
      - .offset:         336
        .size:           2
        .value_kind:     hidden_group_size_z
      - .offset:         338
        .size:           2
        .value_kind:     hidden_remainder_x
      - .offset:         340
        .size:           2
        .value_kind:     hidden_remainder_y
      - .offset:         342
        .size:           2
        .value_kind:     hidden_remainder_z
      - .offset:         360
        .size:           8
        .value_kind:     hidden_global_offset_x
      - .offset:         368
        .size:           8
        .value_kind:     hidden_global_offset_y
      - .offset:         376
        .size:           8
        .value_kind:     hidden_global_offset_z
      - .offset:         384
        .size:           2
        .value_kind:     hidden_grid_dims
      - .offset:         408
        .size:           8
        .value_kind:     hidden_multigrid_sync_arg
      - .offset:         440
        .size:           4
        .value_kind:     hidden_dynamic_lds_size
    .group_segment_fixed_size: 0
    .kernarg_segment_align: 8
    .kernarg_segment_size: 576
    .language:       OpenCL C
    .language_version:
      - 2
      - 0
    .max_flat_workgroup_size: 512
    .name:           _Z6k_mega6Params
    .private_segment_fixed_size: 0
    .sgpr_count:     108
    .sgpr_spill_count: 25
    .symbol:         _Z6k_mega6Params.kd
    .uniform_work_group_size: 1
    .uses_dynamic_stack: false
    .vgpr_count:     245
    .vgpr_spill_count: 0
    .wavefront_size: 64
